# attention tile loops: LDS fragment reads issued directly behind each MFMA (ahead of the softmax VALU) in all three attention modes, on top of MFMA-first tile head and SGPR-base K/V loads
# speedup vs baseline: 1.0102x; 1.0052x over previous
.LBB0_935:
	s_cmp_gt_i32 s41, s30
	s_cselect_b32 s8, s26, s38
	s_mulk_i32 s8, 0x5000
	v_add_u32_e32 v0, s8, v165
	v_add_u32_e32 v80, 0xc800, v0
	s_add_i32 s62, s41, 2
	s_cmp_lt_i32 s62, s65
	s_cselect_b64 s[8:9], -1, 0
	s_and_b64 s[70:71], s[8:9], exec
	s_cselect_b32 s70, s62, s69
	s_ashr_i32 s71, s70, 31
	s_waitcnt lgkmcnt(6)
	v_mfma_f32_32x32x16_bf16 v[2:17], v[126:129], v[102:105], v[2:17]
	s_lshl_b64 s[70:71], s[70:71], 6
	s_add_u32 s39, s70, s5
	v_mov_b32_e32 v62, 0x1340
	s_addc_u32 s40, s71, 0
	v_mad_u64_u32 v[160:161], s[70:71], s39, v62, v[136:137]
	ds_read_b64_tr_b16 v[62:63], v0 offset:61440
	ds_read_b64_tr_b16 v[64:65], v0 offset:64000
	s_mulk_i32 s40, 0x1340
	v_add_u32_e32 v161, s40, v161
	s_mul_i32 s40, s14, 0x5000
	v_add_u32_e32 v142, s40, v131
	ds_read_b64_tr_b16 v[70:71], v0 offset:61504
	ds_read_b64_tr_b16 v[72:73], v0 offset:64064
	s_waitcnt lgkmcnt(8)
	v_mfma_f32_32x32x16_bf16 v[18:33], v[122:125], v[102:105], v[18:33]
	global_load_dwordx4 v[122:125], v[160:161], off offset:3584
	ds_read_b64_tr_b16 v[74:75], v80 offset:15360
	ds_read_b64_tr_b16 v[76:77], v80 offset:17920
	s_waitcnt lgkmcnt(8)
	v_mfma_f32_32x32x16_bf16 v[2:17], v[118:121], v[98:101], v[2:17]
	global_load_dwordx4 v[118:121], v[138:139], off
	v_exp_f32_e32 v0, v158
	v_exp_f32_e32 v79, v159
	v_add_f32_e32 v78, 0, v0
	v_cvt_pk_bf16_f32 v102, v0, v79
	v_exp_f32_e32 v0, v66
	v_add_f32_e32 v78, v79, v78
	v_add_f32_e32 v66, v0, v78
	v_exp_f32_e32 v67, v67
	s_waitcnt lgkmcnt(6)
	v_mfma_f32_32x32x16_bf16 v[18:33], v[114:117], v[98:101], v[18:33]
	ds_read_b64_tr_b16 v[78:79], v80 offset:15424
	ds_read_b64_tr_b16 v[80:81], v80 offset:17984
	v_cvt_pk_bf16_f32 v103, v0, v67
	v_exp_f32_e32 v0, v52
	v_add_f32_e32 v66, v67, v66
	v_add_f32_e32 v52, v0, v66
	v_exp_f32_e32 v53, v53
	s_waitcnt lgkmcnt(6)
	v_mfma_f32_32x32x16_bf16 v[2:17], v[62:65], v[110:113], v[2:17]
	v_add_u32_e32 v158, s15, v164
	ds_read_b128 v[114:117], v158
	v_cvt_pk_bf16_f32 v104, v0, v53
	v_exp_f32_e32 v0, v54
	v_add_f32_e32 v52, v53, v52
	v_add_f32_e32 v52, v0, v52
	v_exp_f32_e32 v53, v55
	s_waitcnt lgkmcnt(5)
	v_mfma_f32_32x32x16_bf16 v[18:33], v[70:73], v[110:113], v[18:33]
	ds_read_b128 v[126:129], v158 offset:4608
	v_exp_f32_e32 v54, v68
	v_cvt_pk_bf16_f32 v105, v0, v53
	v_exp_f32_e32 v0, v69
	v_add_f32_e32 v52, v53, v52
	v_add_f32_e32 v52, v54, v52
	v_cvt_pk_bf16_f32 v98, v54, v0
	v_add_f32_e32 v52, v0, v52
	s_waitcnt lgkmcnt(4)
	v_mfma_f32_32x32x16_bf16 v[2:17], v[74:77], v[106:109], v[2:17]
	ds_read_b128 v[110:113], v158 offset:32
	v_exp_f32_e32 v0, v58
	v_exp_f32_e32 v53, v59
	v_add_f32_e32 v52, v0, v52
	v_cvt_pk_bf16_f32 v99, v0, v53
	v_add_f32_e32 v0, v53, v52
	s_waitcnt lgkmcnt(3)
	v_mfma_f32_32x32x16_bf16 v[18:33], v[78:81], v[106:109], v[18:33]
	ds_read_b128 v[170:173], v158 offset:4640
	v_exp_f32_e32 v52, v56
	v_exp_f32_e32 v53, v57
	v_add_f32_e32 v0, v52, v0
	v_cvt_pk_bf16_f32 v100, v52, v53
	v_add_f32_e32 v0, v53, v0
	s_waitcnt lgkmcnt(3)
	v_mfma_f32_32x32x16_bf16 v[66:81], v[114:117], v[82:85], v[34:49]
	ds_read_b128 v[174:177], v158 offset:64
	ds_read_b128 v[114:117], v158 offset:4672
	v_exp_f32_e32 v52, v60
	v_exp_f32_e32 v53, v61
	v_add_f32_e32 v0, v52, v0
	v_cvt_pk_bf16_f32 v101, v52, v53
	v_add_f32_e32 v0, v53, v0
	v_exp_f32_e32 v106, v50
	v_exp_f32_e32 v107, v51
	v_exp_f32_e32 v108, v144
	v_add_f32_e32 v0, v106, v0
	v_add_f32_e32 v0, v107, v0
	v_cvt_pk_bf16_f32 v106, v106, v107
	v_add_f32_e32 v0, v108, v0
	s_waitcnt lgkmcnt(4)
	v_mfma_f32_32x32x16_bf16 v[50:65], v[126:129], v[82:85], v[34:49]
	s_waitcnt lgkmcnt(3)
	v_mfma_f32_32x32x16_bf16 v[66:81], v[110:113], v[86:89], v[66:81]
	ds_read_b128 v[126:129], v158 offset:96
	v_exp_f32_e32 v107, v145
	v_exp_f32_e32 v109, v146
	v_add_f32_e32 v0, v107, v0
	v_cvt_pk_bf16_f32 v107, v108, v107
	v_add_f32_e32 v0, v109, v0
	v_exp_f32_e32 v108, v147
	v_exp_f32_e32 v110, v148
	ds_read_b128 v[144:147], v158 offset:4704
	s_waitcnt lgkmcnt(4)
	v_mfma_f32_32x32x16_bf16 v[50:65], v[170:173], v[86:89], v[50:65]
	v_add_f32_e32 v0, v108, v0
	v_cvt_pk_bf16_f32 v108, v109, v108
	v_add_f32_e32 v0, v110, v0
	v_exp_f32_e32 v109, v149
	s_waitcnt lgkmcnt(3)
	v_mfma_f32_32x32x16_bf16 v[66:81], v[174:177], v[90:93], v[66:81]
	v_exp_f32_e32 v111, v151
	s_waitcnt vmcnt(1)
	ds_write_b128 v167, v[122:125]
	v_add_f32_e32 v0, v109, v0
	v_cvt_pk_bf16_f32 v109, v110, v109
	v_exp_f32_e32 v110, v150
	s_nop 0
	v_add_f32_e32 v0, v110, v0
	v_add_f32_e32 v0, v111, v0
	v_cvt_pk_bf16_f32 v110, v110, v111
	v_exp_f32_e32 v111, v152
	v_exp_f32_e32 v112, v153
	s_waitcnt lgkmcnt(3)
	v_mfma_f32_32x32x16_bf16 v[50:65], v[114:117], v[90:93], v[50:65]
	v_add_f32_e32 v0, v111, v0
	v_add_f32_e32 v0, v112, v0
	v_cvt_pk_bf16_f32 v111, v111, v112
	s_waitcnt lgkmcnt(2)
	v_mfma_f32_32x32x16_bf16 v[66:81], v[126:129], v[94:97], v[66:81]
	v_exp_f32_e32 v112, v154
	v_exp_f32_e32 v113, v155
	s_waitcnt vmcnt(0)
	ds_write_b128 v142, v[118:121] offset:51200
	v_add_f32_e32 v0, v112, v0
	v_add_f32_e32 v0, v113, v0
	v_cvt_pk_bf16_f32 v112, v112, v113
	v_exp_f32_e32 v113, v156
	v_exp_f32_e32 v114, v157
	s_waitcnt lgkmcnt(2)
	v_mfma_f32_32x32x16_bf16 v[50:65], v[144:147], v[94:97], v[50:65]
	v_add_f32_e32 v0, v113, v0
	v_add_f32_e32 v0, v114, v0
	v_cvt_pk_bf16_f32 v113, v113, v114
	s_mul_i32 s39, s38, 0x5000
	v_med3_i32 v142, v166, 0, v216
	v_add_u32_e32 v116, s39, v165
	v_med3_i32 v145, v166, s46, v217
	v_lshl_add_u32 v142, v142, 2, s27
	ds_read_b64_tr_b16 v[126:127], v116 offset:51200
	ds_read_b64_tr_b16 v[128:129], v116 offset:53760
	ds_read_b64_tr_b16 v[122:123], v116 offset:51264
	ds_read_b64_tr_b16 v[124:125], v116 offset:53824
	ds_read_b64_tr_b16 v[118:119], v116 offset:56320
	ds_read_b64_tr_b16 v[120:121], v116 offset:58880
	ds_read_b64_tr_b16 v[114:115], v116 offset:56384
	ds_read_b64_tr_b16 v[116:117], v116 offset:58944
	ds_read_b32 v144, v142
	v_lshl_add_u32 v142, v145, 2, s27
	ds_read_b32 v146, v142 offset:128
	v_add_u32_e32 v142, 1, v166
	v_med3_i32 v145, v142, 0, v216
	v_lshl_add_u32 v145, v145, 2, s27
	ds_read_b32 v145, v145
	v_med3_i32 v142, v142, s46, v217
	v_cmp_lt_f32_e32 vcc, s66, v0
	s_waitcnt lgkmcnt(0)
	v_pk_add_f32 v[154:155], v[66:67], v[144:145]
	v_lshl_add_u32 v66, v142, 2, s27
	ds_read_b32 v147, v66 offset:128
	s_waitcnt lgkmcnt(0)
	v_pk_add_f32 v[144:145], v[50:51], v[146:147]
	v_add_u32_e32 v50, 2, v166
	v_med3_i32 v51, v50, 0, v216
	v_med3_i32 v66, v50, s46, v217
	v_lshl_add_u32 v50, v51, 2, s27
	v_lshl_add_u32 v51, v66, 2, s27
	ds_read_b32 v146, v51 offset:128
	v_add_u32_e32 v51, 3, v166
	v_med3_i32 v66, v51, 0, v216
	v_med3_i32 v142, v51, s46, v217
	v_lshl_add_u32 v51, v66, 2, s27
	ds_read_b32 v50, v50
	ds_read_b32 v51, v51
	s_waitcnt lgkmcnt(0)
	v_pk_add_f32 v[66:67], v[68:69], v[50:51]
	v_lshl_add_u32 v50, v142, 2, s27
	ds_read_b32 v147, v50 offset:128
	v_add_u32_e32 v50, 8, v166
	v_med3_i32 v51, v50, 0, v216
	s_waitcnt lgkmcnt(0)
	v_pk_add_f32 v[146:147], v[52:53], v[146:147]
	v_med3_i32 v52, v50, s46, v217
	v_lshl_add_u32 v50, v51, 2, s27
	v_lshl_add_u32 v51, v52, 2, s27
	ds_read_b32 v52, v51 offset:128
	v_add_u32_e32 v51, 9, v166
	v_med3_i32 v53, v51, 0, v216
	v_med3_i32 v142, v51, s46, v217
	v_lshl_add_u32 v51, v53, 2, s27
	ds_read_b32 v50, v50
	ds_read_b32 v51, v51
	s_waitcnt lgkmcnt(0)
	v_pk_add_f32 v[68:69], v[70:71], v[50:51]
	v_lshl_add_u32 v50, v142, 2, s27
	ds_read_b32 v53, v50 offset:128
	v_add_u32_e32 v50, 10, v166
	v_med3_i32 v51, v50, 0, v216
	s_waitcnt lgkmcnt(0)
	v_pk_add_f32 v[148:149], v[54:55], v[52:53]
	v_med3_i32 v52, v50, s46, v217
	v_lshl_add_u32 v50, v51, 2, s27
	v_lshl_add_u32 v51, v52, 2, s27
	ds_read_b32 v52, v51 offset:128
	v_add_u32_e32 v51, 11, v166
	v_med3_i32 v53, v51, 0, v216
	v_med3_i32 v54, v51, s46, v217
	v_lshl_add_u32 v51, v53, 2, s27
	ds_read_b32 v50, v50
	ds_read_b32 v51, v51
	s_waitcnt lgkmcnt(0)
	v_pk_add_f32 v[70:71], v[72:73], v[50:51]
	v_lshl_add_u32 v50, v54, 2, s27
	ds_read_b32 v53, v50 offset:128
	v_add_u32_e32 v50, 16, v166
	v_med3_i32 v51, v50, 0, v216
	s_waitcnt lgkmcnt(0)
	v_pk_add_f32 v[150:151], v[56:57], v[52:53]
	v_med3_i32 v52, v50, s46, v217
	v_lshl_add_u32 v50, v51, 2, s27
	v_lshl_add_u32 v51, v52, 2, s27
	ds_read_b32 v52, v51 offset:128
	v_add_u32_e32 v51, 17, v166
	v_med3_i32 v53, v51, 0, v216
	v_med3_i32 v54, v51, s46, v217
	v_lshl_add_u32 v51, v53, 2, s27
	ds_read_b32 v50, v50
	ds_read_b32 v51, v51
	s_waitcnt lgkmcnt(0)
	v_pk_add_f32 v[72:73], v[74:75], v[50:51]
	v_lshl_add_u32 v50, v54, 2, s27
	ds_read_b32 v53, v50 offset:128
	v_add_u32_e32 v50, 18, v166
	v_med3_i32 v51, v50, 0, v216
	s_waitcnt lgkmcnt(0)
	v_pk_add_f32 v[152:153], v[58:59], v[52:53]
	v_med3_i32 v52, v50, s46, v217
	v_lshl_add_u32 v50, v51, 2, s27
	v_lshl_add_u32 v51, v52, 2, s27
	ds_read_b32 v52, v51 offset:128
	v_add_u32_e32 v51, 19, v166
	v_med3_i32 v53, v51, 0, v216
	v_med3_i32 v54, v51, s46, v217
	v_lshl_add_u32 v51, v53, 2, s27
	ds_read_b32 v50, v50
	ds_read_b32 v51, v51
	s_waitcnt lgkmcnt(0)
	v_pk_add_f32 v[74:75], v[76:77], v[50:51]
	v_lshl_add_u32 v50, v54, 2, s27
	ds_read_b32 v53, v50 offset:128
	v_add_u32_e32 v50, 24, v166
	v_med3_i32 v51, v50, 0, v216
	s_waitcnt lgkmcnt(0)
	v_pk_add_f32 v[156:157], v[60:61], v[52:53]
	v_med3_i32 v52, v50, s46, v217
	v_lshl_add_u32 v50, v51, 2, s27
	v_lshl_add_u32 v51, v52, 2, s27
	ds_read_b32 v52, v51 offset:128
	v_add_u32_e32 v51, 25, v166
	v_med3_i32 v53, v51, 0, v216
	v_med3_i32 v54, v51, s46, v217
	v_lshl_add_u32 v51, v53, 2, s27
	ds_read_b32 v50, v50
	ds_read_b32 v51, v51
	s_waitcnt lgkmcnt(0)
	v_pk_add_f32 v[76:77], v[78:79], v[50:51]
	v_lshl_add_u32 v50, v54, 2, s27
	ds_read_b32 v53, v50 offset:128
	v_add_u32_e32 v50, 26, v166
	v_med3_i32 v51, v50, 0, v216
	s_waitcnt lgkmcnt(0)
	v_pk_add_f32 v[158:159], v[62:63], v[52:53]
	v_med3_i32 v52, v50, s46, v217
	v_lshl_add_u32 v50, v51, 2, s27
	v_lshl_add_u32 v51, v52, 2, s27
	ds_read_b32 v52, v51 offset:128
	v_add_u32_e32 v51, 27, v166
	v_med3_i32 v53, v51, 0, v216
	v_med3_i32 v54, v51, s46, v217
	v_lshl_add_u32 v51, v53, 2, s27
	ds_read_b32 v50, v50
	ds_read_b32 v51, v51
	s_waitcnt lgkmcnt(0)
	v_pk_add_f32 v[78:79], v[80:81], v[50:51]
	v_lshl_add_u32 v50, v54, 2, s27
	ds_read_b32 v53, v50 offset:128
	s_waitcnt lgkmcnt(0)
	v_pk_add_f32 v[162:163], v[64:65], v[52:53]
	s_cbranch_vccz .LBB0_937
	v_log_f32_e32 v34, v0
	s_nop 0
	v_floor_f32_e32 v34, v34
	v_cndmask_b32_e32 v34, 0, v34, vcc
	v_mov_b32_e32 v35, v34
	s_nop 1
	v_permlane32_swap_b32_e32 v34, v35
	v_max_f32_e32 v35, v35, v35
	v_max_f32_e32 v34, v34, v34
	v_max_f32_e32 v34, v34, v35
	v_exp_f32_e64 v142, -v34
	v_add_f32_e32 v143, v143, v34
	v_sub_f32_e32 v50, 0, v143
	v_sub_f32_e32 v154, v154, v34
	v_sub_f32_e32 v155, v155, v34
	v_sub_f32_e32 v66, v66, v34
	v_sub_f32_e32 v67, v67, v34
	v_sub_f32_e32 v68, v68, v34
	v_sub_f32_e32 v69, v69, v34
	v_sub_f32_e32 v70, v70, v34
	v_sub_f32_e32 v71, v71, v34
	v_sub_f32_e32 v72, v72, v34
	v_sub_f32_e32 v73, v73, v34
	v_sub_f32_e32 v74, v74, v34
	v_sub_f32_e32 v75, v75, v34
	v_sub_f32_e32 v76, v76, v34
	v_sub_f32_e32 v77, v77, v34
	v_sub_f32_e32 v78, v78, v34
	v_sub_f32_e32 v79, v79, v34
	v_sub_f32_e32 v144, v144, v34
	v_sub_f32_e32 v145, v145, v34
	v_sub_f32_e32 v146, v146, v34
	v_sub_f32_e32 v147, v147, v34
	v_sub_f32_e32 v148, v148, v34
	v_sub_f32_e32 v149, v149, v34
	v_sub_f32_e32 v150, v150, v34
	v_sub_f32_e32 v151, v151, v34
	v_sub_f32_e32 v152, v152, v34
	v_sub_f32_e32 v153, v153, v34
	v_sub_f32_e32 v156, v156, v34
	v_sub_f32_e32 v157, v157, v34
	v_sub_f32_e32 v158, v158, v34
	v_sub_f32_e32 v159, v159, v34
	v_sub_f32_e32 v162, v162, v34
	v_sub_f32_e32 v163, v163, v34
	v_mov_b32_e32 v51, v50
	v_mov_b32_e32 v52, v50
	v_mov_b32_e32 v53, v50
	v_mov_b32_e32 v54, v50
	v_mov_b32_e32 v55, v50
	v_mov_b32_e32 v56, v50
	v_mov_b32_e32 v57, v50
	v_mov_b32_e32 v58, v50
	v_mov_b32_e32 v59, v50
	v_mov_b32_e32 v60, v50
	v_mov_b32_e32 v61, v50
	v_mov_b32_e32 v62, v50
	v_mov_b32_e32 v63, v50
	v_mov_b32_e32 v64, v50
	v_mov_b32_e32 v65, v50
	v_mov_b32_e32 v34, v50
	v_mov_b32_e32 v35, v50
	v_mov_b32_e32 v36, v50
	v_mov_b32_e32 v37, v50
	v_mov_b32_e32 v38, v50
	v_mov_b32_e32 v39, v50
	v_mov_b32_e32 v40, v50
	v_mov_b32_e32 v41, v50
	v_mov_b32_e32 v42, v50
	v_mov_b32_e32 v43, v50
	v_mov_b32_e32 v44, v50
	v_mov_b32_e32 v45, v50
	v_mov_b32_e32 v46, v50
	v_mov_b32_e32 v47, v50
	v_mov_b32_e32 v48, v50
	v_mov_b32_e32 v49, v50
	s_branch .LBB0_938

.LBB0_940:
	s_cmp_lt_i32 s41, s30
	s_cselect_b32 s63, s14, s38
	s_mulk_i32 s63, 0x5000
	v_add_u32_e32 v174, s63, v165
	v_add_u32_e32 v180, 0xc800, v174
	s_add_i32 s41, s41, 3
	v_mfma_f32_32x32x16_bf16 v[2:17], v[126:129], v[102:105], v[2:17]
	ds_read_b64_tr_b16 v[170:171], v174 offset:61440
	ds_read_b64_tr_b16 v[172:173], v174 offset:64000
	ds_read_b64_tr_b16 v[126:127], v174 offset:61504
	ds_read_b64_tr_b16 v[128:129], v174 offset:64064
	s_cmp_lt_i32 s41, s65
	s_cselect_b32 s70, s41, s69
	s_ashr_i32 s71, s70, 31
	s_lshl_b64 s[70:71], s[70:71], 6
	s_add_u32 s41, s70, s5
	s_addc_u32 s63, s71, 0
	v_mov_b32_e32 v80, 0x1340
	s_mulk_i32 s63, 0x1340
	v_mad_u64_u32 v[80:81], s[70:71], s41, v80, v[136:137]
	s_mul_i32 s41, s26, 0x5000
	v_add_u32_e32 v81, s63, v81
	v_add_u32_e32 v182, s41, v131
	v_mfma_f32_32x32x16_bf16 v[18:33], v[122:125], v[102:105], v[18:33]
	global_load_dwordx4 v[122:125], v[80:81], off offset:3584
	ds_read_b64_tr_b16 v[174:175], v180 offset:15360
	ds_read_b64_tr_b16 v[176:177], v180 offset:17920
	v_mfma_f32_32x32x16_bf16 v[2:17], v[118:121], v[98:101], v[2:17]
	global_load_dwordx4 v[118:121], v[160:161], off offset:3840
	v_exp_f32_e32 v80, v154
	v_exp_f32_e32 v102, v155
	v_exp_f32_e32 v66, v66
	v_add_f32_e32 v81, 0, v80
	v_add_f32_e32 v81, v102, v81
	v_cvt_pk_bf16_f32 v102, v80, v102
	v_add_f32_e32 v80, v66, v81
	v_exp_f32_e32 v67, v67
	v_mfma_f32_32x32x16_bf16 v[18:33], v[114:117], v[98:101], v[18:33]
	ds_read_b64_tr_b16 v[178:179], v180 offset:15424
	ds_read_b64_tr_b16 v[180:181], v180 offset:17984
	v_cvt_pk_bf16_f32 v103, v66, v67
	v_exp_f32_e32 v66, v68
	v_add_f32_e32 v80, v67, v80
	v_add_f32_e32 v67, v66, v80
	s_waitcnt lgkmcnt(6)
	v_mfma_f32_32x32x16_bf16 v[2:17], v[170:173], v[106:109], v[2:17]
	ds_read_b128 v[114:117], v168
	v_exp_f32_e32 v68, v69
	v_exp_f32_e32 v69, v70
	v_add_f32_e32 v67, v68, v67
	v_cvt_pk_bf16_f32 v104, v66, v68
	v_add_f32_e32 v66, v69, v67
	v_exp_f32_e32 v67, v71
	s_waitcnt lgkmcnt(5)
	v_mfma_f32_32x32x16_bf16 v[18:33], v[126:129], v[106:109], v[18:33]
	ds_read_b128 v[170:173], v168 offset:4608
	v_exp_f32_e32 v68, v72
	v_add_f32_e32 v66, v67, v66
	v_cvt_pk_bf16_f32 v105, v69, v67
	v_exp_f32_e32 v67, v73
	v_add_f32_e32 v66, v68, v66
	v_add_f32_e32 v66, v67, v66
	v_cvt_pk_bf16_f32 v98, v68, v67
	s_waitcnt lgkmcnt(4)
	v_mfma_f32_32x32x16_bf16 v[2:17], v[174:177], v[110:113], v[2:17]
	ds_read_b128 v[106:109], v168 offset:32
	v_exp_f32_e32 v67, v74
	v_exp_f32_e32 v68, v75
	v_add_f32_e32 v66, v67, v66
	v_cvt_pk_bf16_f32 v99, v67, v68
	v_add_f32_e32 v66, v68, v66
	s_waitcnt lgkmcnt(3)
	v_mfma_f32_32x32x16_bf16 v[18:33], v[178:181], v[110:113], v[18:33]
	ds_read_b128 v[126:129], v168 offset:4640
	ds_read_b128 v[174:177], v168 offset:64
	v_exp_f32_e32 v67, v76
	v_exp_f32_e32 v68, v77
	v_add_f32_e32 v66, v67, v66
	v_cvt_pk_bf16_f32 v100, v67, v68
	v_add_f32_e32 v66, v68, v66
	v_exp_f32_e32 v67, v78
	v_exp_f32_e32 v68, v79
	v_add_f32_e32 v66, v67, v66
	v_cvt_pk_bf16_f32 v101, v67, v68
	v_add_f32_e32 v110, v68, v66
	s_waitcnt lgkmcnt(4)
	v_mfma_f32_32x32x16_bf16 v[66:81], v[114:117], v[82:85], v[50:65]
	s_waitcnt lgkmcnt(3)
	v_mfma_f32_32x32x16_bf16 v[50:65], v[170:173], v[82:85], v[50:65]
	ds_read_b128 v[114:117], v168 offset:4672
	v_exp_f32_e32 v111, v144
	v_exp_f32_e32 v112, v145
	v_exp_f32_e32 v113, v146
	v_add_f32_e32 v110, v111, v110
	v_add_f32_e32 v144, v112, v110
	v_cvt_pk_bf16_f32 v110, v111, v112
	v_add_f32_e32 v111, v113, v144
	s_waitcnt lgkmcnt(3)
	v_mfma_f32_32x32x16_bf16 v[66:81], v[106:109], v[86:89], v[66:81]
	v_exp_f32_e32 v112, v147
	v_exp_f32_e32 v148, v148
	ds_read_b128 v[144:147], v168 offset:96
	v_add_f32_e32 v154, v112, v111
	v_cvt_pk_bf16_f32 v111, v113, v112
	v_add_f32_e32 v112, v148, v154
	s_waitcnt lgkmcnt(3)
	v_mfma_f32_32x32x16_bf16 v[50:65], v[126:129], v[86:89], v[50:65]
	ds_read_b128 v[170:173], v168 offset:4704
	v_exp_f32_e32 v106, v149
	v_exp_f32_e32 v107, v150
	v_add_f32_e32 v108, v106, v112
	v_cvt_pk_bf16_f32 v112, v148, v106
	v_add_f32_e32 v106, v107, v108
	v_exp_f32_e32 v108, v151
	s_waitcnt lgkmcnt(3)
	v_mfma_f32_32x32x16_bf16 v[66:81], v[174:177], v[90:93], v[66:81]
	v_cvt_pk_bf16_f32 v113, v107, v108
	v_exp_f32_e32 v107, v152
	v_add_f32_e32 v106, v108, v106
	v_exp_f32_e32 v108, v153
	v_add_f32_e32 v106, v107, v106
	v_add_f32_e32 v109, v108, v106
	v_cvt_pk_bf16_f32 v106, v107, v108
	v_add_u32_e32 v107, s15, v132
	s_waitcnt vmcnt(1)
	ds_write_b128 v107, v[122:125]
	v_exp_f32_e32 v107, v156
	s_waitcnt lgkmcnt(3)
	v_mfma_f32_32x32x16_bf16 v[50:65], v[114:117], v[90:93], v[50:65]
	v_add_f32_e32 v108, v107, v109
	v_exp_f32_e32 v109, v157
	s_nop 0
	v_add_f32_e32 v108, v109, v108
	v_cvt_pk_bf16_f32 v107, v107, v109
	s_waitcnt lgkmcnt(2)
	v_mfma_f32_32x32x16_bf16 v[66:81], v[144:147], v[94:97], v[66:81]
	v_exp_f32_e32 v109, v158
	v_exp_f32_e32 v114, v159
	s_waitcnt vmcnt(0)
	ds_write_b128 v182, v[118:121] offset:51200
	v_add_f32_e32 v108, v109, v108
	v_add_f32_e32 v115, v114, v108
	v_cvt_pk_bf16_f32 v108, v109, v114
	v_exp_f32_e32 v109, v162
	s_waitcnt lgkmcnt(2)
	v_mfma_f32_32x32x16_bf16 v[50:65], v[170:173], v[94:97], v[50:65]
	v_add_f32_e32 v114, v109, v115
	v_exp_f32_e32 v115, v163
	s_nop 0
	v_add_f32_e32 v160, v115, v114
	v_cvt_pk_bf16_f32 v109, v109, v115
	v_add_u32_e32 v144, 64, v166
	v_med3_i32 v145, v144, 0, v216
	v_med3_i32 v146, v144, s46, v217
	v_add_u32_e32 v116, s40, v165
	v_lshl_add_u32 v144, v145, 2, s27
	v_lshl_add_u32 v145, v146, 2, s27
	ds_read_b64_tr_b16 v[126:127], v116 offset:51200
	ds_read_b64_tr_b16 v[128:129], v116 offset:53760
	ds_read_b64_tr_b16 v[122:123], v116 offset:51264
	ds_read_b64_tr_b16 v[124:125], v116 offset:53824
	ds_read_b64_tr_b16 v[118:119], v116 offset:56320
	ds_read_b64_tr_b16 v[120:121], v116 offset:58880
	ds_read_b64_tr_b16 v[114:115], v116 offset:56384
	ds_read_b64_tr_b16 v[116:117], v116 offset:58944
	ds_read_b32 v146, v145 offset:128
	v_add_u32_e32 v145, 0x41, v166
	v_med3_i32 v147, v145, 0, v216
	v_med3_i32 v148, v145, s46, v217
	v_lshl_add_u32 v145, v147, 2, s27
	ds_read_b32 v144, v144
	ds_read_b32 v145, v145
	s_andn2_b64 vcc, exec, s[8:9]
	s_waitcnt lgkmcnt(0)
	v_pk_add_f32 v[158:159], v[66:67], v[144:145]
	v_lshl_add_u32 v66, v148, 2, s27
	ds_read_b32 v147, v66 offset:128
	v_add_u32_e32 v66, 0x42, v166
	v_med3_i32 v67, v66, 0, v216
	v_med3_i32 v144, v66, s46, v217
	v_lshl_add_u32 v66, v67, 2, s27
	v_lshl_add_u32 v67, v144, 2, s27
	ds_read_b32 v144, v67 offset:128
	v_add_u32_e32 v67, 0x43, v166
	v_med3_i32 v145, v67, 0, v216
	s_waitcnt lgkmcnt(1)
	v_pk_add_f32 v[50:51], v[50:51], v[146:147]
	v_med3_i32 v146, v67, s46, v217
	v_lshl_add_u32 v67, v145, 2, s27
	ds_read_b32 v66, v66
	ds_read_b32 v67, v67
	s_waitcnt lgkmcnt(0)
	v_pk_add_f32 v[66:67], v[68:69], v[66:67]
	v_lshl_add_u32 v68, v146, 2, s27
	ds_read_b32 v145, v68 offset:128
	s_waitcnt lgkmcnt(0)
	v_pk_add_f32 v[144:145], v[52:53], v[144:145]
	v_add_u32_e32 v52, 0x48, v166
	v_med3_i32 v53, v52, 0, v216
	v_med3_i32 v68, v52, s46, v217
	v_lshl_add_u32 v52, v53, 2, s27
	v_lshl_add_u32 v53, v68, 2, s27
	ds_read_b32 v68, v53 offset:128
	v_add_u32_e32 v53, 0x49, v166
	v_med3_i32 v69, v53, 0, v216
	v_med3_i32 v146, v53, s46, v217
	v_lshl_add_u32 v53, v69, 2, s27
	v_lshl_add_u32 v69, v146, 2, s27
	ds_read_b32 v69, v69 offset:128
	ds_read_b32 v52, v52
	ds_read_b32 v53, v53
	s_waitcnt lgkmcnt(2)
	v_pk_add_f32 v[146:147], v[54:55], v[68:69]
	v_add_u32_e32 v54, 0x4a, v166
	v_med3_i32 v55, v54, 0, v216
	v_med3_i32 v68, v54, s46, v217
	v_lshl_add_u32 v54, v55, 2, s27
	v_lshl_add_u32 v55, v68, 2, s27
	ds_read_b32 v54, v54
	ds_read_b32 v68, v55 offset:128
	v_add_u32_e32 v55, 0x4b, v166
	s_waitcnt lgkmcnt(2)
	v_pk_add_f32 v[52:53], v[70:71], v[52:53]
	v_med3_i32 v69, v55, 0, v216
	v_med3_i32 v70, v55, s46, v217
	v_lshl_add_u32 v55, v69, 2, s27
	v_lshl_add_u32 v69, v70, 2, s27
	ds_read_b32 v69, v69 offset:128
	ds_read_b32 v55, v55
	s_waitcnt lgkmcnt(1)
	v_pk_add_f32 v[148:149], v[56:57], v[68:69]
	v_add_u32_e32 v56, 0x50, v166
	v_med3_i32 v57, v56, 0, v216
	v_med3_i32 v68, v56, s46, v217
	v_lshl_add_u32 v56, v57, 2, s27
	v_lshl_add_u32 v57, v68, 2, s27
	ds_read_b32 v70, v57 offset:128
	v_add_u32_e32 v57, 0x51, v166
	v_med3_i32 v68, v57, 0, v216
	v_med3_i32 v71, v57, s46, v217
	v_lshl_add_u32 v57, v68, 2, s27
	ds_read_b32 v56, v56
	ds_read_b32 v57, v57
	s_waitcnt lgkmcnt(3)
	v_pk_add_f32 v[54:55], v[72:73], v[54:55]
	s_waitcnt lgkmcnt(0)
	v_pk_add_f32 v[68:69], v[74:75], v[56:57]
	v_lshl_add_u32 v56, v71, 2, s27
	ds_read_b32 v71, v56 offset:128
	v_add_u32_e32 v56, 0x52, v166
	v_med3_i32 v57, v56, 0, v216
	s_waitcnt lgkmcnt(0)
	v_pk_add_f32 v[150:151], v[58:59], v[70:71]
	v_med3_i32 v58, v56, s46, v217
	v_lshl_add_u32 v56, v57, 2, s27
	v_lshl_add_u32 v57, v58, 2, s27
	ds_read_b32 v70, v57 offset:128
	v_add_u32_e32 v57, 0x53, v166
	v_med3_i32 v58, v57, 0, v216
	v_med3_i32 v71, v57, s46, v217
	v_lshl_add_u32 v57, v58, 2, s27
	ds_read_b32 v56, v56
	ds_read_b32 v57, v57
	s_waitcnt lgkmcnt(0)
	v_pk_add_f32 v[58:59], v[76:77], v[56:57]
	v_lshl_add_u32 v56, v71, 2, s27
	ds_read_b32 v71, v56 offset:128
	v_add_u32_e32 v56, 0x58, v166
	v_med3_i32 v57, v56, 0, v216
	s_waitcnt lgkmcnt(0)
	v_pk_add_f32 v[152:153], v[60:61], v[70:71]
	v_med3_i32 v60, v56, s46, v217
	v_lshl_add_u32 v56, v57, 2, s27
	v_lshl_add_u32 v57, v60, 2, s27
	ds_read_b32 v60, v57 offset:128
	v_add_u32_e32 v57, 0x59, v166
	v_med3_i32 v61, v57, 0, v216
	v_med3_i32 v70, v57, s46, v217
	v_lshl_add_u32 v57, v61, 2, s27
	v_lshl_add_u32 v61, v70, 2, s27
	ds_read_b32 v61, v61 offset:128
	ds_read_b32 v56, v56
	ds_read_b32 v57, v57
	s_waitcnt lgkmcnt(2)
	v_pk_add_f32 v[154:155], v[62:63], v[60:61]
	v_add_u32_e32 v60, 0x5a, v166
	v_med3_i32 v61, v60, 0, v216
	v_med3_i32 v62, v60, s46, v217
	v_lshl_add_u32 v60, v61, 2, s27
	v_lshl_add_u32 v61, v62, 2, s27
	ds_read_b32 v62, v61 offset:128
	v_add_u32_e32 v61, 0x5b, v166
	v_med3_i32 v63, v61, 0, v216
	v_med3_i32 v70, v61, s46, v217
	v_lshl_add_u32 v61, v63, 2, s27
	v_lshl_add_u32 v63, v70, 2, s27
	ds_read_b32 v60, v60
	ds_read_b32 v61, v61
	ds_read_b32 v63, v63 offset:128
	s_waitcnt lgkmcnt(4)
	v_pk_add_f32 v[56:57], v[78:79], v[56:57]
	s_waitcnt lgkmcnt(1)
	v_pk_add_f32 v[60:61], v[80:81], v[60:61]
	s_waitcnt lgkmcnt(0)
	v_pk_add_f32 v[156:157], v[64:65], v[62:63]
	v_mov_b32_e32 v62, 1.0
	s_cbranch_vccnz .LBB0_944
	v_cmp_lt_f32_e32 vcc, s66, v160
	s_cbranch_vccz .LBB0_943
	v_log_f32_e32 v34, v160
	s_nop 0
	v_floor_f32_e32 v34, v34
	v_cndmask_b32_e32 v34, 0, v34, vcc
	v_mov_b32_e32 v35, v34
	s_nop 1
	v_permlane32_swap_b32_e32 v34, v35
	v_max_f32_e32 v35, v35, v35
	v_max_f32_e32 v34, v34, v34
	v_max_f32_e32 v34, v34, v35
	v_exp_f32_e64 v62, -v34
	v_add_f32_e32 v143, v143, v34
	v_sub_f32_e32 v49, 0, v143
	v_sub_f32_e32 v61, v61, v34
	v_sub_f32_e32 v60, v60, v34
	v_sub_f32_e32 v57, v57, v34
	v_sub_f32_e32 v56, v56, v34
	v_sub_f32_e32 v59, v59, v34
	v_sub_f32_e32 v58, v58, v34
	v_sub_f32_e32 v69, v69, v34
	v_sub_f32_e32 v68, v68, v34
	v_sub_f32_e32 v55, v55, v34
	v_sub_f32_e32 v54, v54, v34
	v_sub_f32_e32 v53, v53, v34
	v_sub_f32_e32 v52, v52, v34
	v_sub_f32_e32 v67, v67, v34
	v_sub_f32_e32 v66, v66, v34
	v_sub_f32_e32 v159, v159, v34
	v_sub_f32_e32 v158, v158, v34
	v_sub_f32_e32 v157, v157, v34
	v_sub_f32_e32 v156, v156, v34
	v_sub_f32_e32 v155, v155, v34
	v_sub_f32_e32 v154, v154, v34
	v_sub_f32_e32 v153, v153, v34
	v_sub_f32_e32 v152, v152, v34
	v_sub_f32_e32 v151, v151, v34
	v_sub_f32_e32 v150, v150, v34
	v_sub_f32_e32 v149, v149, v34
	v_sub_f32_e32 v148, v148, v34
	v_sub_f32_e32 v147, v147, v34
	v_sub_f32_e32 v146, v146, v34
	v_sub_f32_e32 v145, v145, v34
	v_sub_f32_e32 v144, v144, v34
	v_sub_f32_e32 v51, v51, v34
	v_sub_f32_e32 v50, v50, v34
	v_mov_b32_e32 v48, v49
	v_mov_b32_e32 v47, v49
	v_mov_b32_e32 v46, v49
	v_mov_b32_e32 v45, v49
	v_mov_b32_e32 v44, v49
	v_mov_b32_e32 v43, v49
	v_mov_b32_e32 v42, v49
	v_mov_b32_e32 v41, v49
	v_mov_b32_e32 v40, v49
	v_mov_b32_e32 v39, v49
	v_mov_b32_e32 v38, v49
	v_mov_b32_e32 v37, v49
	v_mov_b32_e32 v36, v49
	v_mov_b32_e32 v35, v49
	v_mov_b32_e32 v34, v49
	s_branch .LBB0_944

.LBB0_959:
	s_add_i32 s41, s41, 2
	s_cmp_gt_u32 s41, 1
	s_cselect_b32 s30, s40, s62
	s_mulk_i32 s30, 0x5000
	v_add_u32_e32 v142, s30, v197
	v_add_u32_e32 v158, 0xc800, v142
	s_waitcnt lgkmcnt(6)
	v_mfma_f32_32x32x16_bf16 v[18:33], v[106:109], v[138:141], v[18:33]
	ds_read_b64_tr_b16 v[110:111], v142 offset:61440
	ds_read_b64_tr_b16 v[112:113], v142 offset:64000
	s_mul_i32 s63, s39, 0x5000
	s_add_i32 s30, s63, 0
	s_waitcnt lgkmcnt(6)
	v_mfma_f32_32x32x16_bf16 v[2:17], v[102:105], v[138:141], v[2:17]
	ds_read_b64_tr_b16 v[106:107], v142 offset:61504
	ds_read_b64_tr_b16 v[108:109], v142 offset:64064
	v_lshl_add_u64 v[102:103], s[4:5], 0, v[186:187]
	global_load_dwordx4 v[154:157], v[102:103], off
	v_lshl_add_u64 v[102:103], s[4:5], 0, v[184:185]
	global_load_dwordx4 v[146:149], v[102:103], off
	v_lshl_add_u64 v[102:103], s[4:5], 0, v[182:183]
	global_load_dwordx4 v[150:153], v[102:103], off
	v_lshl_add_u64 v[192:193], s[0:1], 0, v[180:181]
	s_mov_b32 s65, 0x10000
	v_add_co_u32_e32 v102, vcc, s65, v192
	v_lshl_add_u64 v[194:195], s[0:1], 0, v[178:179]
	s_nop 0
	v_addc_co_u32_e32 v103, vcc, 0, v193, vcc
	v_add_co_u32_e32 v104, vcc, s65, v194
	s_waitcnt lgkmcnt(6)
	v_mfma_f32_32x32x16_bf16 v[18:33], v[94:97], v[98:101], v[18:33]
	v_addc_co_u32_e32 v105, vcc, 0, v195, vcc
	global_load_dwordx4 v[138:141], v[102:103], off
	global_load_dwordx4 v[142:145], v[104:105], off
	ds_read_b64_tr_b16 v[102:103], v158 offset:15360
	ds_read_b64_tr_b16 v[104:105], v158 offset:17920
	v_exp_f32_e32 v66, v66
	v_exp_f32_e32 v67, v67
	v_add_f32_e32 v94, 0, v66
	v_cvt_pk_bf16_f32 v66, v66, v67
	v_add_f32_e32 v159, v67, v94
	s_waitcnt lgkmcnt(6)
	v_mfma_f32_32x32x16_bf16 v[2:17], v[90:93], v[98:101], v[2:17]
	ds_read_b64_tr_b16 v[94:95], v158 offset:15424
	ds_read_b64_tr_b16 v[96:97], v158 offset:17984
	v_exp_f32_e32 v67, v68
	v_exp_f32_e32 v68, v69
	v_add_f32_e32 v69, v67, v159
	v_add_f32_e32 v69, v68, v69
	v_cvt_pk_bf16_f32 v67, v67, v68
	s_waitcnt lgkmcnt(6)
	v_mfma_f32_32x32x16_bf16 v[18:33], v[110:113], v[82:85], v[18:33]
	ds_read_b128 v[90:93], v206
	v_exp_f32_e32 v68, v70
	v_exp_f32_e32 v70, v71
	v_add_f32_e32 v69, v68, v69
	v_add_f32_e32 v69, v70, v69
	v_cvt_pk_bf16_f32 v68, v68, v70
	s_waitcnt lgkmcnt(5)
	v_mfma_f32_32x32x16_bf16 v[2:17], v[106:109], v[82:85], v[2:17]
	ds_read_b128 v[158:161], v206 offset:12800
	v_exp_f32_e32 v70, v72
	v_exp_f32_e32 v71, v73
	v_add_f32_e32 v69, v70, v69
	v_add_f32_e32 v72, v71, v69
	v_cvt_pk_bf16_f32 v69, v70, v71
	s_waitcnt lgkmcnt(4)
	v_mfma_f32_32x32x16_bf16 v[18:33], v[102:105], v[86:89], v[18:33]
	ds_read_b128 v[162:165], v206 offset:32
	v_exp_f32_e32 v70, v74
	s_nop 0
	v_add_f32_e32 v71, v70, v72
	v_exp_f32_e32 v72, v75
	s_waitcnt lgkmcnt(3)
	v_mfma_f32_32x32x16_bf16 v[2:17], v[94:97], v[86:89], v[2:17]
	ds_read_b128 v[220:223], v206 offset:12832
	v_add_f32_e32 v71, v72, v71
	v_cvt_pk_bf16_f32 v70, v70, v72
	v_exp_f32_e32 v72, v76
	s_nop 0
	v_add_f32_e32 v71, v72, v71
	s_waitcnt lgkmcnt(3)
	v_mfma_f32_32x32x16_bf16 v[98:113], v[90:93], v[114:117], v[50:65]
	ds_read_b128 v[224:227], v206 offset:64
	v_exp_f32_e32 v73, v77
	v_exp_f32_e32 v74, v78
	v_add_f32_e32 v75, v73, v71
	v_cvt_pk_bf16_f32 v71, v72, v73
	v_add_f32_e32 v72, v74, v75
	s_waitcnt lgkmcnt(3)
	v_mfma_f32_32x32x16_bf16 v[82:97], v[158:161], v[114:117], v[50:65]
	v_exp_f32_e32 v73, v79
	v_exp_f32_e32 v75, v80
	ds_read_b128 v[76:79], v206 offset:12864
	v_add_f32_e32 v80, v73, v72
	v_cvt_pk_bf16_f32 v72, v74, v73
	v_add_f32_e32 v73, v75, v80
	s_waitcnt lgkmcnt(3)
	v_mfma_f32_32x32x16_bf16 v[98:113], v[162:165], v[118:121], v[98:113]
	ds_read_b128 v[158:161], v206 offset:96
	v_exp_f32_e32 v74, v81
	s_nop 0
	v_add_f32_e32 v80, v74, v73
	v_cvt_pk_bf16_f32 v73, v75, v74
	s_waitcnt lgkmcnt(3)
	v_mfma_f32_32x32x16_bf16 v[82:97], v[220:223], v[118:121], v[82:97]
	ds_read_b128 v[162:165], v206 offset:12896
	v_exp_f32_e32 v34, v34
	v_exp_f32_e32 v35, v35
	v_add_f32_e32 v74, v34, v80
	v_add_f32_e32 v75, v35, v74
	v_cvt_pk_bf16_f32 v74, v34, v35
	s_waitcnt lgkmcnt(3)
	v_mfma_f32_32x32x16_bf16 v[98:113], v[224:227], v[122:125], v[98:113]
	ds_read_b128 v[220:223], v206 offset:128
	v_exp_f32_e32 v34, v36
	v_exp_f32_e32 v36, v37
	v_add_f32_e32 v35, v34, v75
	v_add_f32_e32 v80, v36, v35
	v_cvt_pk_bf16_f32 v75, v34, v36
	s_waitcnt lgkmcnt(3)
	v_mfma_f32_32x32x16_bf16 v[82:97], v[76:79], v[122:125], v[82:97]
	ds_read_b128 v[34:37], v206 offset:12928
	v_exp_f32_e32 v38, v38
	v_exp_f32_e32 v39, v39
	v_add_f32_e32 v76, v38, v80
	v_add_f32_e32 v77, v39, v76
	v_cvt_pk_bf16_f32 v76, v38, v39
	s_waitcnt lgkmcnt(3)
	v_mfma_f32_32x32x16_bf16 v[98:113], v[158:161], v[126:129], v[98:113]
	ds_read_b128 v[224:227], v206 offset:160
	v_exp_f32_e32 v38, v40
	v_exp_f32_e32 v40, v41
	v_add_f32_e32 v39, v38, v77
	v_add_f32_e32 v78, v40, v39
	v_cvt_pk_bf16_f32 v77, v38, v40
	s_waitcnt lgkmcnt(3)
	v_mfma_f32_32x32x16_bf16 v[82:97], v[162:165], v[126:129], v[82:97]
	ds_read_b128 v[38:41], v206 offset:12960
	v_exp_f32_e32 v42, v42
	s_nop 0
	v_add_f32_e32 v78, v42, v78
	s_waitcnt lgkmcnt(3)
	v_mfma_f32_32x32x16_bf16 v[98:113], v[220:223], v[130:133], v[98:113]
	v_exp_f32_e32 v43, v43
	s_waitcnt vmcnt(4)
	ds_write_b128 v202, v[154:157] offset:25600
	s_waitcnt vmcnt(3)
	ds_write_b128 v200, v[146:149] offset:25600
	s_waitcnt vmcnt(2)
	ds_write_b128 v201, v[150:153] offset:25600
	v_add_f32_e32 v79, v43, v78
	v_cvt_pk_bf16_f32 v78, v42, v43
	v_exp_f32_e32 v42, v44
	s_nop 0
	v_add_f32_e32 v43, v42, v79
	s_waitcnt lgkmcnt(5)
	v_mfma_f32_32x32x16_bf16 v[82:97], v[34:37], v[130:133], v[82:97]
	v_exp_f32_e32 v34, v45
	s_nop 0
	v_add_f32_e32 v35, v34, v43
	v_cvt_pk_bf16_f32 v79, v42, v34
	v_exp_f32_e32 v34, v46
	s_nop 0
	v_add_f32_e32 v35, v34, v35
	s_waitcnt lgkmcnt(4)
	v_mfma_f32_32x32x16_bf16 v[98:113], v[224:227], v[134:137], v[98:113]
	v_exp_f32_e32 v36, v47
	s_nop 0
	v_cvt_pk_bf16_f32 v80, v34, v36
	v_exp_f32_e32 v34, v48
	v_add_f32_e32 v35, v36, v35
	v_add_u32_e32 v36, s30, v204
	s_waitcnt vmcnt(1)
	ds_write_b128 v36, v[138:141] offset:51200
	v_add_u32_e32 v36, s30, v205
	v_add_f32_e32 v35, v34, v35
	s_waitcnt vmcnt(0)
	ds_write_b128 v36, v[142:145] offset:51200
	s_waitcnt lgkmcnt(5)
	v_mfma_f32_32x32x16_bf16 v[82:97], v[38:41], v[134:137], v[82:97]
	v_exp_f32_e32 v36, v49
	s_nop 0
	v_add_f32_e32 v209, v36, v35
	v_cvt_pk_bf16_f32 v81, v34, v36
	s_mul_i32 s30, s62, 0x5000
	v_add_u32_e32 v138, s30, v197
	ds_read_b64_tr_b16 v[148:149], v138 offset:51200
	ds_read_b64_tr_b16 v[150:151], v138 offset:53760
	ds_read_b64_tr_b16 v[146:147], v138 offset:53824
	ds_read_b64_tr_b16 v[144:145], v138 offset:51264
	ds_read_b64_tr_b16 v[152:153], v138 offset:56320
	ds_read_b64_tr_b16 v[154:155], v138 offset:58880
	ds_read_b64_tr_b16 v[142:143], v138 offset:58944
	ds_read_b64_tr_b16 v[140:141], v138 offset:56384
	v_cmp_lt_f32_e32 vcc, s66, v209
	s_cbranch_vccz .LBB0_961
	v_log_f32_e32 v34, v209
	s_nop 0
	v_floor_f32_e32 v34, v34
	v_cndmask_b32_e32 v34, 0, v34, vcc
	v_mov_b32_e32 v35, v34
	s_nop 1
	v_permlane32_swap_b32_e32 v34, v35
	v_max_f32_e32 v35, v35, v35
	v_max_f32_e32 v34, v34, v34
	v_max_f32_e32 v35, v34, v35
	v_exp_f32_e64 v190, -v35
	v_add_f32_e32 v207, v207, v35
	v_sub_f32_e32 v34, 0, v207
	v_sub_f32_e32 v113, v113, v35
	v_sub_f32_e32 v112, v112, v35
	v_sub_f32_e32 v111, v111, v35
	v_sub_f32_e32 v110, v110, v35
	v_sub_f32_e32 v109, v109, v35
	v_sub_f32_e32 v108, v108, v35
	v_sub_f32_e32 v107, v107, v35
	v_sub_f32_e32 v106, v106, v35
	v_sub_f32_e32 v105, v105, v35
	v_sub_f32_e32 v104, v104, v35
	v_sub_f32_e32 v103, v103, v35
	v_sub_f32_e32 v102, v102, v35
	v_sub_f32_e32 v101, v101, v35
	v_sub_f32_e32 v100, v100, v35
	v_sub_f32_e32 v99, v99, v35
	v_sub_f32_e32 v98, v98, v35
	v_sub_f32_e32 v97, v97, v35
	v_sub_f32_e32 v96, v96, v35
	v_sub_f32_e32 v95, v95, v35
	v_sub_f32_e32 v94, v94, v35
	v_sub_f32_e32 v93, v93, v35
	v_sub_f32_e32 v92, v92, v35
	v_sub_f32_e32 v91, v91, v35
	v_sub_f32_e32 v90, v90, v35
	v_sub_f32_e32 v89, v89, v35
	v_sub_f32_e32 v88, v88, v35
	v_sub_f32_e32 v87, v87, v35
	v_sub_f32_e32 v86, v86, v35
	v_sub_f32_e32 v85, v85, v35
	v_sub_f32_e32 v84, v84, v35
	v_sub_f32_e32 v83, v83, v35
	v_sub_f32_e32 v82, v82, v35
	v_mov_b32_e32 v35, v34
	v_mov_b32_e32 v36, v34
	v_mov_b32_e32 v37, v34
	v_mov_b32_e32 v38, v34
	v_mov_b32_e32 v39, v34
	v_mov_b32_e32 v40, v34
	v_mov_b32_e32 v41, v34
	v_mov_b32_e32 v42, v34
	v_mov_b32_e32 v43, v34
	v_mov_b32_e32 v44, v34
	v_mov_b32_e32 v45, v34
	v_mov_b32_e32 v46, v34
	v_mov_b32_e32 v47, v34
	v_mov_b32_e32 v48, v34
	v_mov_b32_e32 v49, v34
	v_mov_b32_e32 v50, v34
	v_mov_b32_e32 v51, v34
	v_mov_b32_e32 v52, v34
	v_mov_b32_e32 v53, v34
	v_mov_b32_e32 v54, v34
	v_mov_b32_e32 v55, v34
	v_mov_b32_e32 v56, v34
	v_mov_b32_e32 v57, v34
	v_mov_b32_e32 v58, v34
	v_mov_b32_e32 v59, v34
	v_mov_b32_e32 v60, v34
	v_mov_b32_e32 v61, v34
	v_mov_b32_e32 v62, v34
	v_mov_b32_e32 v63, v34
	v_mov_b32_e32 v64, v34
	v_mov_b32_e32 v65, v34
	s_branch .LBB0_962

.LBB0_964:
	v_add_u32_e32 v139, 0xc800, v138
	s_nop 0
	v_mfma_f32_32x32x16_bf16 v[18:33], v[148:151], v[66:69], v[18:33]
	ds_read_b64_tr_b16 v[220:221], v138 offset:61440
	ds_read_b64_tr_b16 v[222:223], v138 offset:64000
	s_min_u32 s30, s41, 0x7e
	s_lshl_b32 s30, s30, 6
	s_add_i32 s30, s38, s30
	s_mulk_i32 s30, 0x180
	s_lshl_b64 s[70:71], s[30:31], 1
	s_add_u32 s70, s26, s70
	s_mul_i32 s30, s40, 0x5000
	s_addc_u32 s71, s27, s71
	s_add_i32 s30, s30, 0
	v_mfma_f32_32x32x16_bf16 v[2:17], v[144:147], v[66:69], v[2:17]
	ds_read_b64_tr_b16 v[224:225], v138 offset:61504
	ds_read_b64_tr_b16 v[226:227], v138 offset:64064
	v_lshl_add_u64 v[66:67], v[168:169], 1, s[70:71]
	global_load_dwordx4 v[164:167], v[66:67], off
	v_lshl_add_u64 v[66:67], v[174:175], 1, s[70:71]
	global_load_dwordx4 v[156:159], v[66:67], off
	v_lshl_add_u64 v[66:67], v[176:177], 1, s[70:71]
	global_load_dwordx4 v[160:163], v[66:67], off
	s_mov_b32 s65, 0x18000
	v_add_co_u32_e32 v66, vcc, s65, v192
	v_mfma_f32_32x32x16_bf16 v[18:33], v[152:155], v[70:73], v[18:33]
	s_nop 0
	v_addc_co_u32_e32 v67, vcc, 0, v193, vcc
	v_add_co_u32_e32 v68, vcc, s65, v194
	v_exp_f32_e32 v98, v98
	s_nop 0
	v_addc_co_u32_e32 v69, vcc, 0, v195, vcc
	global_load_dwordx4 v[144:147], v[66:67], off
	global_load_dwordx4 v[148:151], v[68:69], off
	ds_read_b64_tr_b16 v[66:67], v139 offset:15360
	ds_read_b64_tr_b16 v[68:69], v139 offset:17920
	v_exp_f32_e32 v99, v99
	v_add_f32_e32 v138, 0, v98
	v_add_f32_e32 v152, v99, v138
	v_cvt_pk_bf16_f32 v138, v98, v99
	v_mfma_f32_32x32x16_bf16 v[2:17], v[140:143], v[70:73], v[2:17]
	ds_read_b64_tr_b16 v[98:99], v139 offset:15424
	v_exp_f32_e32 v153, v100
	v_exp_f32_e32 v154, v101
	ds_read_b64_tr_b16 v[100:101], v139 offset:17984
	v_add_f32_e32 v139, v153, v152
	v_add_f32_e32 v192, v154, v139
	v_cvt_pk_bf16_f32 v139, v153, v154
	s_waitcnt lgkmcnt(6)
	v_mfma_f32_32x32x16_bf16 v[18:33], v[220:223], v[74:77], v[18:33]
	ds_read_b128 v[152:155], v206 offset:25600
	v_exp_f32_e32 v70, v102
	v_exp_f32_e32 v72, v103
	v_add_f32_e32 v71, v70, v192
	v_add_f32_e32 v71, v72, v71
	v_cvt_pk_bf16_f32 v140, v70, v72
	s_waitcnt lgkmcnt(5)
	v_mfma_f32_32x32x16_bf16 v[2:17], v[224:227], v[74:77], v[2:17]
	ds_read_b128 v[192:195], v206 offset:38400
	v_exp_f32_e32 v70, v104
	v_exp_f32_e32 v72, v105
	v_add_f32_e32 v71, v70, v71
	v_add_f32_e32 v71, v72, v71
	v_cvt_pk_bf16_f32 v141, v70, v72
	s_waitcnt lgkmcnt(4)
	v_mfma_f32_32x32x16_bf16 v[18:33], v[66:69], v[78:81], v[18:33]
	ds_read_b128 v[102:105], v206 offset:25632
	v_exp_f32_e32 v66, v106
	s_nop 0
	v_add_f32_e32 v67, v66, v71
	v_exp_f32_e32 v68, v107
	s_waitcnt lgkmcnt(3)
	v_mfma_f32_32x32x16_bf16 v[2:17], v[98:101], v[78:81], v[2:17]
	ds_read_b128 v[220:223], v206 offset:38432
	v_cvt_pk_bf16_f32 v98, v66, v68
	v_exp_f32_e32 v66, v108
	v_add_f32_e32 v67, v68, v67
	v_add_f32_e32 v67, v66, v67
	v_exp_f32_e32 v68, v109
	v_exp_f32_e32 v100, v110
	ds_read_b128 v[106:109], v206 offset:25664
	v_add_f32_e32 v67, v68, v67
	v_cvt_pk_bf16_f32 v99, v66, v68
	v_add_f32_e32 v101, v100, v67
	s_waitcnt lgkmcnt(4)
	v_mfma_f32_32x32x16_bf16 v[66:81], v[152:155], v[114:117], v[34:49]
	s_waitcnt lgkmcnt(3)
	v_mfma_f32_32x32x16_bf16 v[34:49], v[192:195], v[114:117], v[34:49]
	ds_read_b128 v[152:155], v206 offset:38464
	v_exp_f32_e32 v110, v111
	v_exp_f32_e32 v142, v112
	v_add_f32_e32 v101, v110, v101
	v_cvt_pk_bf16_f32 v100, v100, v110
	v_add_f32_e32 v101, v142, v101
	s_waitcnt lgkmcnt(3)
	v_mfma_f32_32x32x16_bf16 v[66:81], v[102:105], v[118:121], v[66:81]
	v_exp_f32_e32 v143, v113
	ds_read_b128 v[110:113], v206 offset:25696
	v_add_f32_e32 v192, v143, v101
	v_cvt_pk_bf16_f32 v101, v142, v143
	s_waitcnt lgkmcnt(3)
	v_mfma_f32_32x32x16_bf16 v[34:49], v[220:223], v[118:121], v[34:49]
	ds_read_b128 v[102:105], v206 offset:38496
	v_exp_f32_e32 v82, v82
	v_exp_f32_e32 v83, v83
	v_add_f32_e32 v142, v82, v192
	v_cvt_pk_bf16_f32 v82, v82, v83
	v_add_f32_e32 v142, v83, v142
	s_waitcnt lgkmcnt(3)
	v_mfma_f32_32x32x16_bf16 v[66:81], v[106:109], v[122:125], v[66:81]
	ds_read_b128 v[192:195], v206 offset:25728
	v_exp_f32_e32 v83, v84
	v_exp_f32_e32 v85, v85
	v_add_f32_e32 v84, v83, v142
	v_add_f32_e32 v84, v85, v84
	v_cvt_pk_bf16_f32 v83, v83, v85
	s_waitcnt lgkmcnt(3)
	v_mfma_f32_32x32x16_bf16 v[34:49], v[152:155], v[122:125], v[34:49]
	ds_read_b128 v[106:109], v206 offset:38528
	v_exp_f32_e32 v85, v86
	v_exp_f32_e32 v86, v87
	v_add_f32_e32 v84, v85, v84
	v_add_f32_e32 v87, v86, v84
	v_cvt_pk_bf16_f32 v84, v85, v86
	v_exp_f32_e32 v85, v88
	s_waitcnt lgkmcnt(3)
	v_mfma_f32_32x32x16_bf16 v[66:81], v[110:113], v[126:129], v[66:81]
	ds_read_b128 v[152:155], v206 offset:25760
	v_add_f32_e32 v86, v85, v87
	v_exp_f32_e32 v87, v89
	s_nop 0
	v_add_f32_e32 v86, v87, v86
	v_cvt_pk_bf16_f32 v85, v85, v87
	s_waitcnt lgkmcnt(3)
	v_mfma_f32_32x32x16_bf16 v[34:49], v[102:105], v[126:129], v[34:49]
	ds_read_b128 v[110:113], v206 offset:38560
	v_exp_f32_e32 v87, v90
	s_nop 0
	v_add_f32_e32 v86, v87, v86
	v_exp_f32_e32 v88, v91
	s_waitcnt lgkmcnt(3)
	v_mfma_f32_32x32x16_bf16 v[66:81], v[192:195], v[130:133], v[66:81]
	s_waitcnt vmcnt(4)
	ds_write_b128 v202, v[164:167]
	s_waitcnt vmcnt(3)
	ds_write_b128 v200, v[156:159]
	s_waitcnt vmcnt(2)
	ds_write_b128 v201, v[160:163]
	v_add_f32_e32 v89, v88, v86
	v_cvt_pk_bf16_f32 v86, v87, v88
	v_exp_f32_e32 v87, v92
	s_nop 0
	v_add_f32_e32 v88, v87, v89
	v_exp_f32_e32 v89, v93
	s_waitcnt lgkmcnt(5)
	v_mfma_f32_32x32x16_bf16 v[34:49], v[106:109], v[130:133], v[34:49]
	v_add_f32_e32 v88, v89, v88
	v_cvt_pk_bf16_f32 v87, v87, v89
	v_exp_f32_e32 v89, v94
	s_nop 0
	v_add_f32_e32 v88, v89, v88
	v_exp_f32_e32 v90, v95
	s_waitcnt lgkmcnt(4)
	v_mfma_f32_32x32x16_bf16 v[66:81], v[152:155], v[134:137], v[66:81]
	v_add_f32_e32 v91, v90, v88
	v_cvt_pk_bf16_f32 v88, v89, v90
	v_exp_f32_e32 v89, v96
	s_nop 0
	v_add_f32_e32 v90, v89, v91
	v_add_u32_e32 v91, s30, v204
	s_waitcnt vmcnt(1)
	ds_write_b128 v91, v[144:147] offset:51200
	v_add_u32_e32 v91, s30, v205
	s_waitcnt vmcnt(0)
	ds_write_b128 v91, v[148:151] offset:51200
	s_waitcnt lgkmcnt(5)
	v_mfma_f32_32x32x16_bf16 v[34:49], v[110:113], v[134:137], v[34:49]
	v_exp_f32_e32 v91, v97
	s_nop 0
	v_add_f32_e32 v143, v91, v90
	v_cvt_pk_bf16_f32 v89, v89, v91
	v_add_u32_e32 v90, s63, v197
	ds_read_b64_tr_b16 v[106:107], v90 offset:51200
	ds_read_b64_tr_b16 v[108:109], v90 offset:53760
	ds_read_b64_tr_b16 v[104:105], v90 offset:53824
	ds_read_b64_tr_b16 v[102:103], v90 offset:51264
	ds_read_b64_tr_b16 v[94:95], v90 offset:56320
	ds_read_b64_tr_b16 v[96:97], v90 offset:58880
	ds_read_b64_tr_b16 v[92:93], v90 offset:58944
	ds_read_b64_tr_b16 v[90:91], v90 offset:56384
	v_cmp_lt_f32_e32 vcc, s66, v143
	s_cbranch_vccz .LBB0_966
	v_log_f32_e32 v50, v143
	s_nop 0
	v_floor_f32_e32 v50, v50
	v_cndmask_b32_e32 v50, 0, v50, vcc
	v_mov_b32_e32 v51, v50
	s_nop 1
	v_permlane32_swap_b32_e32 v50, v51
	v_max_f32_e32 v51, v51, v51
	v_max_f32_e32 v50, v50, v50
	v_max_f32_e32 v51, v50, v51
	v_exp_f32_e64 v142, -v51
	v_add_f32_e32 v207, v207, v51
	v_sub_f32_e32 v50, 0, v207
	v_sub_f32_e32 v81, v81, v51
	v_sub_f32_e32 v80, v80, v51
	v_sub_f32_e32 v79, v79, v51
	v_sub_f32_e32 v78, v78, v51
	v_sub_f32_e32 v77, v77, v51
	v_sub_f32_e32 v76, v76, v51
	v_sub_f32_e32 v75, v75, v51
	v_sub_f32_e32 v74, v74, v51
	v_sub_f32_e32 v73, v73, v51
	v_sub_f32_e32 v72, v72, v51
	v_sub_f32_e32 v71, v71, v51
	v_sub_f32_e32 v70, v70, v51
	v_sub_f32_e32 v69, v69, v51
	v_sub_f32_e32 v68, v68, v51
	v_sub_f32_e32 v67, v67, v51
	v_sub_f32_e32 v66, v66, v51
	v_sub_f32_e32 v49, v49, v51
	v_sub_f32_e32 v48, v48, v51
	v_sub_f32_e32 v47, v47, v51
	v_sub_f32_e32 v46, v46, v51
	v_sub_f32_e32 v45, v45, v51
	v_sub_f32_e32 v44, v44, v51
	v_sub_f32_e32 v43, v43, v51
	v_sub_f32_e32 v42, v42, v51
	v_sub_f32_e32 v41, v41, v51
	v_sub_f32_e32 v40, v40, v51
	v_sub_f32_e32 v39, v39, v51
	v_sub_f32_e32 v38, v38, v51
	v_sub_f32_e32 v37, v37, v51
	v_sub_f32_e32 v36, v36, v51
	v_sub_f32_e32 v35, v35, v51
	v_sub_f32_e32 v34, v34, v51
	v_mov_b32_e32 v51, v50
	v_mov_b32_e32 v52, v50
	v_mov_b32_e32 v53, v50
	v_mov_b32_e32 v54, v50
	v_mov_b32_e32 v55, v50
	v_mov_b32_e32 v56, v50
	v_mov_b32_e32 v57, v50
	v_mov_b32_e32 v58, v50
	v_mov_b32_e32 v59, v50
	v_mov_b32_e32 v60, v50
	v_mov_b32_e32 v61, v50
	v_mov_b32_e32 v62, v50
	v_mov_b32_e32 v63, v50
	v_mov_b32_e32 v64, v50
	v_mov_b32_e32 v65, v50
	s_branch .LBB0_967

.LBB0_985:
	s_waitcnt lgkmcnt(3)
	v_mfma_f32_32x32x16_bf16 v[50:65], v[158:161], v[142:145], v[50:65]
	s_add_i32 s52, s73, s75
	s_add_i32 s0, s75, 0xffffff80
	s_add_i32 s37, s52, 0xffffff80
	s_cmp_lt_i32 s0, s70
	s_cselect_b64 s[6:7], -1, 0
	s_sub_i32 s0, s52, 64
	s_cmpk_gt_i32 s0, 0xff66
	s_cselect_b64 s[0:1], -1, 0
	s_add_i32 s36, s52, 0xffffffa1
	s_cmpk_gt_i32 s36, 0x5a
	s_cselect_b64 s[4:5], -1, 0
	s_cmp_gt_u32 s76, 1
	s_cselect_b32 s53, s74, s77
	s_mulk_i32 s53, 0x5000
	s_cmpk_gt_i32 s37, 0xff66
	v_add_u32_e32 v180, s53, v192
	s_cselect_b64 s[78:79], -1, 0
	v_add_u32_e32 v199, 0xc800, v180
	s_and_b64 s[6:7], s[78:79], s[6:7]
	ds_read_b64_tr_b16 v[200:201], v180 offset:56320
	ds_read_b64_tr_b16 v[202:203], v180 offset:58880
	s_mul_i32 s78, s72, 0x5000
	s_add_i32 s37, s78, 0
	v_mov_b32_e32 v83, v82
	v_mov_b32_e32 v84, v82
	v_mov_b32_e32 v85, v82
	v_mov_b32_e32 v86, v82
	s_waitcnt lgkmcnt(4)
	v_mfma_f32_32x32x16_bf16 v[34:49], v[154:157], v[142:145], v[34:49]
	ds_read_b64_tr_b16 v[204:205], v180 offset:56384
	ds_read_b64_tr_b16 v[206:207], v180 offset:58944
	v_mov_b32_e32 v87, v82
	v_mov_b32_e32 v88, v82
	v_mov_b32_e32 v89, v82
	v_mov_b32_e32 v90, v82
	s_waitcnt lgkmcnt(5)
	v_mfma_f32_32x32x16_bf16 v[18:33], v[150:153], v[142:145], v[18:33]
	ds_read_b64_tr_b16 v[208:209], v180 offset:56448
	ds_read_b64_tr_b16 v[210:211], v180 offset:59008
	v_mov_b32_e32 v91, v82
	v_mov_b32_e32 v92, v82
	v_mov_b32_e32 v93, v82
	v_mov_b32_e32 v94, v82
	s_waitcnt lgkmcnt(6)
	v_mfma_f32_32x32x16_bf16 v[2:17], v[146:149], v[142:145], v[2:17]
	ds_read_b64_tr_b16 v[220:221], v180 offset:56512
	ds_read_b64_tr_b16 v[222:223], v180 offset:59072
	v_mov_b32_e32 v95, v82
	v_mov_b32_e32 v96, v82
	v_mov_b32_e32 v97, v82
	s_waitcnt lgkmcnt(6)
	v_mfma_f32_32x32x16_bf16 v[50:65], v[200:203], v[138:141], v[50:65]
	ds_read_b64_tr_b16 v[146:147], v180 offset:61440
	ds_read_b64_tr_b16 v[148:149], v180 offset:64000
	v_exp_f32_e32 v98, v98
	v_exp_f32_e32 v99, v99
	v_add_f32_e32 v142, 0, v98
	v_add_f32_e32 v143, v99, v142
	v_cvt_pk_bf16_f32 v142, v98, v99
	s_waitcnt lgkmcnt(6)
	v_mfma_f32_32x32x16_bf16 v[34:49], v[204:207], v[138:141], v[34:49]
	ds_read_b64_tr_b16 v[200:201], v180 offset:61504
	ds_read_b64_tr_b16 v[202:203], v180 offset:64064
	v_exp_f32_e32 v98, v100
	v_exp_f32_e32 v100, v101
	v_add_f32_e32 v99, v98, v143
	v_add_f32_e32 v144, v100, v99
	v_cvt_pk_bf16_f32 v143, v98, v100
	s_waitcnt lgkmcnt(6)
	v_mfma_f32_32x32x16_bf16 v[18:33], v[208:211], v[138:141], v[18:33]
	ds_read_b64_tr_b16 v[98:99], v180 offset:61568
	ds_read_b64_tr_b16 v[100:101], v180 offset:64128
	v_exp_f32_e32 v102, v102
	s_nop 0
	v_add_f32_e32 v144, v102, v144
	v_exp_f32_e32 v103, v103
	s_waitcnt lgkmcnt(6)
	v_mfma_f32_32x32x16_bf16 v[2:17], v[220:223], v[138:141], v[2:17]
	ds_read_b64_tr_b16 v[204:205], v180 offset:61632
	ds_read_b64_tr_b16 v[206:207], v180 offset:64192
	v_add_f32_e32 v145, v103, v144
	v_cvt_pk_bf16_f32 v144, v102, v103
	v_exp_f32_e32 v102, v104
	s_nop 0
	v_add_f32_e32 v103, v102, v145
	s_waitcnt lgkmcnt(6)
	v_mfma_f32_32x32x16_bf16 v[50:65], v[146:149], v[134:137], v[50:65]
	ds_read_b64_tr_b16 v[208:209], v199 offset:15360
	ds_read_b64_tr_b16 v[210:211], v199 offset:17920
	v_exp_f32_e32 v104, v105
	s_nop 0
	v_add_f32_e32 v138, v104, v103
	v_cvt_pk_bf16_f32 v145, v102, v104
	s_waitcnt lgkmcnt(6)
	v_mfma_f32_32x32x16_bf16 v[34:49], v[200:203], v[134:137], v[34:49]
	ds_read_b64_tr_b16 v[102:103], v199 offset:15424
	ds_read_b64_tr_b16 v[104:105], v199 offset:17984
	v_exp_f32_e32 v106, v106
	v_exp_f32_e32 v107, v107
	v_add_f32_e32 v138, v106, v138
	v_add_f32_e32 v139, v107, v138
	v_cvt_pk_bf16_f32 v138, v106, v107
	s_waitcnt lgkmcnt(6)
	v_mfma_f32_32x32x16_bf16 v[18:33], v[98:101], v[134:137], v[18:33]
	ds_read_b64_tr_b16 v[146:147], v199 offset:15488
	ds_read_b64_tr_b16 v[148:149], v199 offset:18048
	v_exp_f32_e32 v98, v108
	v_exp_f32_e32 v100, v109
	v_add_f32_e32 v99, v98, v139
	v_add_f32_e32 v106, v100, v99
	v_cvt_pk_bf16_f32 v139, v98, v100
	s_waitcnt lgkmcnt(6)
	v_mfma_f32_32x32x16_bf16 v[2:17], v[204:207], v[134:137], v[2:17]
	ds_read_b64_tr_b16 v[98:99], v199 offset:15552
	ds_read_b64_tr_b16 v[100:101], v199 offset:18112
	v_exp_f32_e32 v107, v110
	s_nop 0
	v_add_f32_e32 v106, v107, v106
	v_exp_f32_e32 v108, v111
	s_waitcnt lgkmcnt(6)
	v_mfma_f32_32x32x16_bf16 v[50:65], v[208:211], v[130:133], v[50:65]
	ds_read_b128 v[200:203], v196
	v_cvt_pk_bf16_f32 v140, v107, v108
	v_exp_f32_e32 v107, v112
	v_add_f32_e32 v106, v108, v106
	v_add_f32_e32 v106, v107, v106
	s_waitcnt lgkmcnt(5)
	v_mfma_f32_32x32x16_bf16 v[34:49], v[102:105], v[130:133], v[34:49]
	ds_read_b128 v[204:207], v196 offset:8704
	v_exp_f32_e32 v108, v113
	s_nop 0
	v_add_f32_e32 v106, v108, v106
	v_cvt_pk_bf16_f32 v141, v107, v108
	s_waitcnt lgkmcnt(4)
	v_mfma_f32_32x32x16_bf16 v[18:33], v[146:149], v[130:133], v[18:33]
	ds_read_b128 v[208:211], v196 offset:32
	v_exp_f32_e32 v66, v66
	v_exp_f32_e32 v67, v67
	v_add_f32_e32 v102, v66, v106
	v_add_f32_e32 v102, v67, v102
	v_cvt_pk_bf16_f32 v134, v66, v67
	s_waitcnt lgkmcnt(3)
	v_mfma_f32_32x32x16_bf16 v[2:17], v[98:101], v[130:133], v[2:17]
	ds_read_b128 v[146:149], v196 offset:8736
	v_exp_f32_e32 v66, v68
	v_exp_f32_e32 v68, v69
	v_add_f32_e32 v67, v66, v102
	v_add_f32_e32 v98, v68, v67
	v_cvt_pk_bf16_f32 v135, v66, v68
	v_exp_f32_e32 v70, v70
	ds_read_b128 v[66:69], v196 offset:64
	v_add_f32_e32 v130, v70, v98
	s_waitcnt lgkmcnt(4)
	v_mfma_f32_32x32x16_bf16 v[98:113], v[200:203], v[114:117], v[82:97]
	s_waitcnt lgkmcnt(3)
	v_mfma_f32_32x32x16_bf16 v[82:97], v[204:207], v[114:117], v[82:97]
	ds_read_b128 v[200:203], v196 offset:8768
	v_exp_f32_e32 v71, v71
	s_nop 0
	v_cvt_pk_bf16_f32 v136, v70, v71
	v_exp_f32_e32 v70, v72
	v_add_f32_e32 v130, v71, v130
	v_add_f32_e32 v71, v70, v130
	s_waitcnt lgkmcnt(3)
	v_mfma_f32_32x32x16_bf16 v[98:113], v[208:211], v[118:121], v[98:113]
	ds_read_b128 v[204:207], v196 offset:96
	v_exp_f32_e32 v72, v73
	s_nop 0
	v_add_f32_e32 v130, v72, v71
	v_cvt_pk_bf16_f32 v137, v70, v72
	s_waitcnt lgkmcnt(3)
	v_mfma_f32_32x32x16_bf16 v[82:97], v[146:149], v[118:121], v[82:97]
	ds_read_b128 v[70:73], v196 offset:8800
	v_exp_f32_e32 v74, v74
	v_exp_f32_e32 v75, v75
	v_add_f32_e32 v130, v74, v130
	v_add_f32_e32 v131, v75, v130
	v_cvt_pk_bf16_f32 v130, v74, v75
	s_waitcnt lgkmcnt(3)
	v_mfma_f32_32x32x16_bf16 v[98:113], v[66:69], v[122:125], v[98:113]
	v_exp_f32_e32 v66, v76
	v_exp_f32_e32 v68, v77
	s_waitcnt vmcnt(3)
	ds_write_b128 v190, v[228:231] offset:25600
	s_waitcnt vmcnt(2)
	ds_write_b128 v188, v[232:235] offset:25600
	v_add_f32_e32 v67, v66, v131
	v_cvt_pk_bf16_f32 v131, v66, v68
	v_add_f32_e32 v67, v68, v67
	s_waitcnt lgkmcnt(4)
	v_mfma_f32_32x32x16_bf16 v[82:97], v[200:203], v[122:125], v[82:97]
	v_exp_f32_e32 v66, v78
	s_nop 0
	v_add_f32_e32 v67, v66, v67
	s_waitcnt lgkmcnt(3)
	v_mfma_f32_32x32x16_bf16 v[98:113], v[204:207], v[126:129], v[98:113]
	v_exp_f32_e32 v68, v79
	s_nop 0
	v_cvt_pk_bf16_f32 v132, v66, v68
	v_exp_f32_e32 v66, v80
	v_add_f32_e32 v67, v68, v67
	v_add_u32_e32 v68, s37, v176
	s_waitcnt vmcnt(1)
	ds_write_b128 v68, v[236:239] offset:51200
	v_add_u32_e32 v68, s37, v178
	v_add_f32_e32 v67, v66, v67
	s_waitcnt vmcnt(0)
	ds_write_b128 v68, v[240:243] offset:51200
	s_cmpk_lt_u32 s76, 0x7f
	s_cselect_b32 s84, 0x4d000, 0
	s_add_u32 s84, s84, s88
	s_add_u32 s84, s8, s84
	s_addc_u32 s85, s9, 0
	s_add_u32 s98, s8, s88
	s_addc_u32 s99, s9, 0
	global_load_dwordx4 v[228:231], v168, s[84:85] offset:1024
	global_load_dwordx4 v[232:235], v170, s[84:85] offset:1024
	global_load_dwordx4 v[236:239], v168, s[98:99] offset:2048
	global_load_dwordx4 v[240:243], v170, s[98:99] offset:2048
	s_waitcnt lgkmcnt(4)
	v_mfma_f32_32x32x16_bf16 v[82:97], v[70:73], v[126:129], v[82:97]
	v_exp_f32_e32 v68, v81
	s_nop 0
	v_add_f32_e32 v199, v68, v67
	v_cvt_pk_bf16_f32 v133, v66, v68
	s_mul_i32 s37, s77, 0x5000
	v_add_u32_e32 v201, s37, v192
	ds_read_b64_tr_b16 v[158:159], v201 offset:51200
	ds_read_b64_tr_b16 v[154:155], v201 offset:51264
	ds_read_b64_tr_b16 v[150:151], v201 offset:51328
	ds_read_b64_tr_b16 v[146:147], v201 offset:51392
	ds_read_b64_tr_b16 v[160:161], v201 offset:53760
	ds_read_b64_tr_b16 v[156:157], v201 offset:53824
	ds_read_b64_tr_b16 v[152:153], v201 offset:53888
	ds_read_b64_tr_b16 v[148:149], v201 offset:53952
	s_andn2_b64 vcc, exec, s[6:7]
	v_add_u32_e32 v200, s75, v179
	s_cbranch_vccnz .LBB0_987
	v_add_u32_e32 v66, 0x80, v200
	v_med3_i32 v67, v66, 0, v216
	v_med3_i32 v66, v66, s46, v217
	v_lshl_add_u32 v68, v66, 2, s15
	v_add_u32_e32 v66, 0x81, v200
	v_med3_i32 v69, v66, 0, v216
	v_med3_i32 v66, v66, s46, v217
	v_lshl_add_u32 v70, v66, 2, s15
	v_add_u32_e32 v66, 0x82, v200
	v_med3_i32 v71, v66, 0, v216
	v_med3_i32 v66, v66, s46, v217
	v_lshl_add_u32 v72, v66, 2, s15
	v_add_u32_e32 v66, 0x83, v200
	v_med3_i32 v73, v66, 0, v216
	v_med3_i32 v66, v66, s46, v217
	v_lshl_add_u32 v67, v67, 2, s15
	v_lshl_add_u32 v69, v69, 2, s15
	v_lshl_add_u32 v71, v71, 2, s15
	v_lshl_add_u32 v73, v73, 2, s15
	v_lshl_add_u32 v74, v66, 2, s15
	ds_read_b32 v66, v67
	ds_read_b32 v68, v68 offset:128
	ds_read_b32 v67, v69
	ds_read_b32 v69, v70 offset:128
	ds_read_b32 v70, v71
	ds_read_b32 v72, v72 offset:128
	ds_read_b32 v71, v73
	ds_read_b32 v73, v74 offset:128
	v_add_u32_e32 v74, 0x88, v200
	v_med3_i32 v75, v74, 0, v216
	v_med3_i32 v74, v74, s46, v217
	v_lshl_add_u32 v76, v74, 2, s15
	v_add_u32_e32 v74, 0x89, v200
	v_med3_i32 v77, v74, 0, v216
	v_med3_i32 v74, v74, s46, v217
	v_lshl_add_u32 v78, v74, 2, s15
	v_add_u32_e32 v74, 0x8a, v200
	v_med3_i32 v79, v74, 0, v216
	v_med3_i32 v74, v74, s46, v217
	v_lshl_add_u32 v80, v74, 2, s15
	v_add_u32_e32 v74, 0x8b, v200
	v_med3_i32 v81, v74, 0, v216
	v_med3_i32 v74, v74, s46, v217
	v_lshl_add_u32 v75, v75, 2, s15
	v_lshl_add_u32 v77, v77, 2, s15
	v_lshl_add_u32 v79, v79, 2, s15
	v_lshl_add_u32 v81, v81, 2, s15
	v_lshl_add_u32 v162, v74, 2, s15
	ds_read_b32 v74, v75
	ds_read_b32 v76, v76 offset:128
	ds_read_b32 v75, v77
	ds_read_b32 v77, v78 offset:128
	ds_read_b32 v78, v79
	ds_read_b32 v80, v80 offset:128
	ds_read_b32 v79, v81
	ds_read_b32 v81, v162 offset:128
	v_add_u32_e32 v162, 0x90, v200
	v_med3_i32 v163, v162, 0, v216
	v_med3_i32 v162, v162, s46, v217
	v_lshl_add_u32 v164, v162, 2, s15
	v_add_u32_e32 v162, 0x91, v200
	v_med3_i32 v165, v162, 0, v216
	v_med3_i32 v162, v162, s46, v217
	v_lshl_add_u32 v180, v162, 2, s15
	v_add_u32_e32 v162, 0x92, v200
	v_med3_i32 v202, v162, 0, v216
	v_med3_i32 v162, v162, s46, v217
	v_add_u32_e32 v207, 0x99, v200
	v_lshl_add_u32 v203, v162, 2, s15
	v_add_u32_e32 v162, 0x93, v200
	v_med3_i32 v208, v207, 0, v216
	v_med3_i32 v207, v207, s46, v217
	v_med3_i32 v204, v162, 0, v216
	v_lshl_add_u32 v214, v207, 2, s15
	v_add_u32_e32 v207, 0x9a, v200
	v_lshl_add_u32 v163, v163, 2, s15
	v_lshl_add_u32 v165, v165, 2, s15
	v_lshl_add_u32 v202, v202, 2, s15
	v_med3_i32 v162, v162, s46, v217
	v_lshl_add_u32 v205, v204, 2, s15
	v_lshl_add_u32 v209, v208, 2, s15
	v_med3_i32 v208, v207, 0, v216
	v_med3_i32 v207, v207, s46, v217
	v_lshl_add_u32 v206, v162, 2, s15
	ds_read_b32 v162, v163
	ds_read_b32 v164, v164 offset:128
	ds_read_b32 v163, v165
	ds_read_b32 v165, v180 offset:128
	ds_read_b32 v202, v202
	ds_read_b32 v204, v203 offset:128
	ds_read_b32 v203, v205
	ds_read_b32 v205, v206 offset:128
	v_add_u32_e32 v180, 0x98, v200
	v_lshl_add_u32 v212, v207, 2, s15
	v_add_u32_e32 v207, 0x9b, v200
	v_med3_i32 v206, v180, 0, v216
	v_lshl_add_u32 v210, v208, 2, s15
	v_med3_i32 v208, v207, 0, v216
	v_med3_i32 v207, v207, s46, v217
	v_med3_i32 v180, v180, s46, v217
	v_lshl_add_u32 v206, v206, 2, s15
	v_lshl_add_u32 v211, v208, 2, s15
	v_lshl_add_u32 v213, v207, 2, s15
	v_lshl_add_u32 v180, v180, 2, s15
	ds_read_b32 v206, v206
	ds_read_b32 v208, v180 offset:128
	ds_read_b32 v210, v210
	ds_read_b32 v211, v211
	ds_read_b32 v207, v209
	ds_read_b32 v213, v213 offset:128
	ds_read_b32 v212, v212 offset:128
	ds_read_b32 v209, v214 offset:128
	s_waitcnt lgkmcnt(4)
	v_pk_add_f32 v[112:113], v[112:113], v[210:211]
	s_waitcnt lgkmcnt(3)
	v_pk_add_f32 v[110:111], v[110:111], v[206:207]
	v_pk_add_f32 v[108:109], v[108:109], v[202:203]
	v_pk_add_f32 v[106:107], v[106:107], v[162:163]
	v_pk_add_f32 v[104:105], v[104:105], v[78:79]
	v_pk_add_f32 v[102:103], v[102:103], v[74:75]
	v_pk_add_f32 v[100:101], v[100:101], v[70:71]
	v_pk_add_f32 v[98:99], v[98:99], v[66:67]
	s_waitcnt lgkmcnt(1)
	v_pk_add_f32 v[96:97], v[96:97], v[212:213]
	s_waitcnt lgkmcnt(0)
	v_pk_add_f32 v[94:95], v[94:95], v[208:209]
	v_pk_add_f32 v[92:93], v[92:93], v[204:205]
	v_pk_add_f32 v[90:91], v[90:91], v[164:165]
	v_pk_add_f32 v[88:89], v[88:89], v[80:81]
	v_pk_add_f32 v[86:87], v[86:87], v[76:77]
	v_pk_add_f32 v[84:85], v[84:85], v[72:73]
	v_pk_add_f32 v[82:83], v[82:83], v[68:69]

.LBB0_992:
	v_mfma_f32_32x32x16_bf16 v[50:65], v[158:161], v[142:145], v[50:65]
	s_cmpk_lt_i32 s36, 0x5b
	s_cselect_b64 s[36:37], -1, 0
	s_add_i32 s6, s75, 0xffffff40
	s_addk_i32 s52, 0xff40
	s_cmpk_lt_i32 s52, 0xfea7
	s_cselect_b64 s[4:5], -1, 0
	s_cmp_gt_i32 s6, s71
	s_cselect_b64 s[6:7], -1, 0
	v_add_u32_e32 v210, 0xc800, v201
	s_cmpk_gt_u32 s76, 0x7e
	s_cselect_b64 s[52:53], -1, 0
	ds_read_b64_tr_b16 v[202:203], v201 offset:56320
	ds_read_b64_tr_b16 v[204:205], v201 offset:58880
	s_mul_i32 s79, s74, 0x5000
	s_add_i32 s79, s79, 0
	v_mov_b32_e32 v68, v67
	v_mov_b32_e32 v69, v67
	v_mov_b32_e32 v70, v67
	v_mov_b32_e32 v71, v67
	v_mfma_f32_32x32x16_bf16 v[34:49], v[154:157], v[142:145], v[34:49]
	ds_read_b64_tr_b16 v[206:207], v201 offset:56384
	ds_read_b64_tr_b16 v[208:209], v201 offset:58944
	ds_read_b64_tr_b16 v[220:221], v201 offset:56448
	ds_read_b64_tr_b16 v[222:223], v201 offset:59008
	v_mov_b32_e32 v72, v67
	v_mov_b32_e32 v73, v67
	v_mov_b32_e32 v74, v67
	v_mov_b32_e32 v75, v67
	v_mfma_f32_32x32x16_bf16 v[18:33], v[150:153], v[142:145], v[18:33]
	v_mov_b32_e32 v76, v67
	v_mov_b32_e32 v77, v67
	v_mov_b32_e32 v78, v67
	v_mov_b32_e32 v79, v67
	v_mfma_f32_32x32x16_bf16 v[2:17], v[146:149], v[142:145], v[2:17]
	ds_read_b64_tr_b16 v[182:183], v201 offset:56512
	ds_read_b64_tr_b16 v[184:185], v201 offset:59072
	v_mov_b32_e32 v80, v67
	v_mov_b32_e32 v81, v67
	s_waitcnt lgkmcnt(6)
	v_mfma_f32_32x32x16_bf16 v[50:65], v[202:205], v[138:141], v[50:65]
	ds_read_b64_tr_b16 v[146:147], v201 offset:61440
	ds_read_b64_tr_b16 v[148:149], v201 offset:64000
	v_exp_f32_e32 v98, v98
	v_exp_f32_e32 v99, v99
	v_add_f32_e32 v142, 0, v98
	v_add_f32_e32 v143, v99, v142
	v_cvt_pk_bf16_f32 v142, v98, v99
	s_waitcnt lgkmcnt(6)
	v_mfma_f32_32x32x16_bf16 v[34:49], v[206:209], v[138:141], v[34:49]
	ds_read_b64_tr_b16 v[202:203], v201 offset:61504
	ds_read_b64_tr_b16 v[204:205], v201 offset:64064
	v_exp_f32_e32 v98, v100
	v_exp_f32_e32 v100, v101
	v_add_f32_e32 v99, v98, v143
	v_add_f32_e32 v144, v100, v99
	v_cvt_pk_bf16_f32 v143, v98, v100
	s_waitcnt lgkmcnt(6)
	v_mfma_f32_32x32x16_bf16 v[18:33], v[220:223], v[138:141], v[18:33]
	ds_read_b64_tr_b16 v[98:99], v201 offset:61568
	ds_read_b64_tr_b16 v[100:101], v201 offset:64128
	v_exp_f32_e32 v102, v102
	s_nop 0
	v_add_f32_e32 v144, v102, v144
	v_exp_f32_e32 v103, v103
	s_waitcnt lgkmcnt(6)
	v_mfma_f32_32x32x16_bf16 v[2:17], v[182:185], v[138:141], v[2:17]
	ds_read_b64_tr_b16 v[206:207], v201 offset:61632
	ds_read_b64_tr_b16 v[208:209], v201 offset:64192
	v_add_f32_e32 v145, v103, v144
	v_cvt_pk_bf16_f32 v144, v102, v103
	v_exp_f32_e32 v102, v104
	s_nop 0
	v_add_f32_e32 v103, v102, v145
	s_waitcnt lgkmcnt(6)
	v_mfma_f32_32x32x16_bf16 v[50:65], v[146:149], v[134:137], v[50:65]
	ds_read_b64_tr_b16 v[182:183], v210 offset:15360
	ds_read_b64_tr_b16 v[184:185], v210 offset:17920
	v_exp_f32_e32 v104, v105
	s_nop 0
	v_add_f32_e32 v138, v104, v103
	v_cvt_pk_bf16_f32 v145, v102, v104
	s_waitcnt lgkmcnt(6)
	v_mfma_f32_32x32x16_bf16 v[34:49], v[202:205], v[134:137], v[34:49]
	ds_read_b64_tr_b16 v[102:103], v210 offset:15424
	ds_read_b64_tr_b16 v[104:105], v210 offset:17984
	v_exp_f32_e32 v106, v106
	v_exp_f32_e32 v107, v107
	v_add_f32_e32 v138, v106, v138
	v_add_f32_e32 v139, v107, v138
	v_cvt_pk_bf16_f32 v138, v106, v107
	s_waitcnt lgkmcnt(6)
	v_mfma_f32_32x32x16_bf16 v[18:33], v[98:101], v[134:137], v[18:33]
	ds_read_b64_tr_b16 v[146:147], v210 offset:15488
	ds_read_b64_tr_b16 v[148:149], v210 offset:18048
	v_exp_f32_e32 v98, v108
	v_exp_f32_e32 v100, v109
	v_add_f32_e32 v99, v98, v139
	v_add_f32_e32 v106, v100, v99
	v_cvt_pk_bf16_f32 v139, v98, v100
	s_waitcnt lgkmcnt(6)
	v_mfma_f32_32x32x16_bf16 v[2:17], v[206:209], v[134:137], v[2:17]
	ds_read_b64_tr_b16 v[98:99], v210 offset:15552
	ds_read_b64_tr_b16 v[100:101], v210 offset:18112
	v_exp_f32_e32 v107, v110
	s_nop 0
	v_add_f32_e32 v106, v107, v106
	v_exp_f32_e32 v108, v111
	s_waitcnt lgkmcnt(6)
	v_mfma_f32_32x32x16_bf16 v[50:65], v[182:185], v[130:133], v[50:65]
	ds_read_b128 v[202:205], v196 offset:25600
	v_cvt_pk_bf16_f32 v140, v107, v108
	v_exp_f32_e32 v107, v112
	v_add_f32_e32 v106, v108, v106
	v_add_f32_e32 v106, v107, v106
	s_waitcnt lgkmcnt(5)
	v_mfma_f32_32x32x16_bf16 v[34:49], v[102:105], v[130:133], v[34:49]
	ds_read_b128 v[182:185], v196 offset:34304
	v_exp_f32_e32 v108, v113
	s_nop 0
	v_add_f32_e32 v106, v108, v106
	v_cvt_pk_bf16_f32 v141, v107, v108
	s_waitcnt lgkmcnt(4)
	v_mfma_f32_32x32x16_bf16 v[18:33], v[146:149], v[130:133], v[18:33]
	ds_read_b128 v[206:209], v196 offset:25632
	v_exp_f32_e32 v82, v82
	v_exp_f32_e32 v83, v83
	v_add_f32_e32 v102, v82, v106
	v_add_f32_e32 v102, v83, v102
	v_cvt_pk_bf16_f32 v134, v82, v83
	s_waitcnt lgkmcnt(3)
	v_mfma_f32_32x32x16_bf16 v[2:17], v[98:101], v[130:133], v[2:17]
	ds_read_b128 v[146:149], v196 offset:34336
	v_exp_f32_e32 v82, v84
	v_exp_f32_e32 v84, v85
	v_add_f32_e32 v83, v82, v102
	v_add_f32_e32 v98, v84, v83
	v_cvt_pk_bf16_f32 v135, v82, v84
	v_exp_f32_e32 v86, v86
	ds_read_b128 v[82:85], v196 offset:25664
	v_add_f32_e32 v130, v86, v98
	s_waitcnt lgkmcnt(4)
	v_mfma_f32_32x32x16_bf16 v[98:113], v[202:205], v[114:117], v[66:81]
	s_waitcnt lgkmcnt(3)
	v_mfma_f32_32x32x16_bf16 v[66:81], v[182:185], v[114:117], v[66:81]
	ds_read_b128 v[202:205], v196 offset:34368
	v_exp_f32_e32 v87, v87
	s_nop 0
	v_cvt_pk_bf16_f32 v136, v86, v87
	v_exp_f32_e32 v86, v88
	v_add_f32_e32 v130, v87, v130
	v_add_f32_e32 v87, v86, v130
	s_waitcnt lgkmcnt(3)
	v_mfma_f32_32x32x16_bf16 v[98:113], v[206:209], v[118:121], v[98:113]
	ds_read_b128 v[182:185], v196 offset:25696
	v_exp_f32_e32 v88, v89
	s_nop 0
	v_add_f32_e32 v130, v88, v87
	v_cvt_pk_bf16_f32 v137, v86, v88
	s_waitcnt lgkmcnt(3)
	v_mfma_f32_32x32x16_bf16 v[66:81], v[146:149], v[118:121], v[66:81]
	ds_read_b128 v[86:89], v196 offset:34400
	v_exp_f32_e32 v90, v90
	v_exp_f32_e32 v91, v91
	v_add_f32_e32 v130, v90, v130
	v_add_f32_e32 v131, v91, v130
	v_cvt_pk_bf16_f32 v130, v90, v91
	s_waitcnt lgkmcnt(3)
	v_mfma_f32_32x32x16_bf16 v[98:113], v[82:85], v[122:125], v[98:113]
	v_exp_f32_e32 v82, v92
	v_exp_f32_e32 v84, v93
	s_waitcnt vmcnt(3)
	ds_write_b128 v190, v[228:231]
	s_waitcnt vmcnt(2)
	ds_write_b128 v188, v[232:235]
	v_add_f32_e32 v83, v82, v131
	v_cvt_pk_bf16_f32 v131, v82, v84
	v_add_f32_e32 v83, v84, v83
	s_waitcnt lgkmcnt(4)
	v_mfma_f32_32x32x16_bf16 v[66:81], v[202:205], v[122:125], v[66:81]
	v_exp_f32_e32 v82, v94
	s_nop 0
	v_add_f32_e32 v83, v82, v83
	s_waitcnt lgkmcnt(3)
	v_mfma_f32_32x32x16_bf16 v[98:113], v[182:185], v[126:129], v[98:113]
	v_exp_f32_e32 v84, v95
	s_nop 0
	v_cvt_pk_bf16_f32 v132, v82, v84
	v_exp_f32_e32 v82, v96
	v_add_f32_e32 v83, v84, v83
	v_add_u32_e32 v84, s79, v176
	s_waitcnt vmcnt(1)
	ds_write_b128 v84, v[236:239] offset:51200
	v_add_u32_e32 v84, s79, v178
	v_add_f32_e32 v83, v82, v83
	s_waitcnt vmcnt(0)
	ds_write_b128 v84, v[240:243] offset:51200
	s_cmpk_lt_u32 s76, 0x7f
	s_cselect_b32 s84, s67, 0
	s_cselect_b32 s98, 0x4d000, 0
	s_add_u32 s84, s84, s88
	s_add_u32 s98, s98, s88
	s_add_u32 s84, s8, s84
	s_addc_u32 s85, s9, 0
	s_add_u32 s98, s8, s98
	s_addc_u32 s99, s9, 0
	global_load_dwordx4 v[228:231], v168, s[84:85] offset:1024
	global_load_dwordx4 v[232:235], v170, s[84:85] offset:1024
	global_load_dwordx4 v[236:239], v168, s[98:99] offset:2048
	global_load_dwordx4 v[240:243], v170, s[98:99] offset:2048
	s_waitcnt lgkmcnt(4)
	v_mfma_f32_32x32x16_bf16 v[66:81], v[86:89], v[126:129], v[66:81]
	v_exp_f32_e32 v84, v97
	s_nop 0
	v_add_f32_e32 v163, v84, v83
	v_cvt_pk_bf16_f32 v133, v82, v84
	v_add_u32_e32 v82, s78, v192
	ds_read_b64_tr_b16 v[158:159], v82 offset:51200
	ds_read_b64_tr_b16 v[154:155], v82 offset:51264
	ds_read_b64_tr_b16 v[150:151], v82 offset:51328
	ds_read_b64_tr_b16 v[146:147], v82 offset:51392
	ds_read_b64_tr_b16 v[160:161], v82 offset:53760
	ds_read_b64_tr_b16 v[156:157], v82 offset:53824
	ds_read_b64_tr_b16 v[152:153], v82 offset:53888
	ds_read_b64_tr_b16 v[148:149], v82 offset:53952
	s_and_b64 s[0:1], s[0:1], s[36:37]
	s_andn2_b64 vcc, exec, s[0:1]
	s_cbranch_vccnz .LBB0_994
	v_add_u32_e32 v82, 0xc0, v200
	v_med3_i32 v83, v82, 0, v216
	v_med3_i32 v82, v82, s46, v217
	v_lshl_add_u32 v84, v82, 2, s15
	v_add_u32_e32 v82, 0xc1, v200
	v_med3_i32 v85, v82, 0, v216
	v_med3_i32 v82, v82, s46, v217
	v_lshl_add_u32 v86, v82, 2, s15
	v_add_u32_e32 v82, 0xc2, v200
	v_med3_i32 v87, v82, 0, v216
	v_med3_i32 v82, v82, s46, v217
	v_lshl_add_u32 v88, v82, 2, s15
	v_add_u32_e32 v82, 0xc3, v200
	v_med3_i32 v89, v82, 0, v216
	v_med3_i32 v82, v82, s46, v217
	v_lshl_add_u32 v83, v83, 2, s15
	v_lshl_add_u32 v85, v85, 2, s15
	v_lshl_add_u32 v87, v87, 2, s15
	v_lshl_add_u32 v89, v89, 2, s15
	v_lshl_add_u32 v90, v82, 2, s15
	ds_read_b32 v82, v83
	ds_read_b32 v84, v84 offset:128
	ds_read_b32 v83, v85
	ds_read_b32 v85, v86 offset:128
	ds_read_b32 v86, v87
	ds_read_b32 v88, v88 offset:128
	ds_read_b32 v87, v89
	ds_read_b32 v89, v90 offset:128
	v_add_u32_e32 v90, 0xc8, v200
	v_med3_i32 v91, v90, 0, v216
	v_med3_i32 v90, v90, s46, v217
	v_lshl_add_u32 v92, v90, 2, s15
	v_add_u32_e32 v90, 0xc9, v200
	v_med3_i32 v93, v90, 0, v216
	v_med3_i32 v90, v90, s46, v217
	v_lshl_add_u32 v94, v90, 2, s15
	v_add_u32_e32 v90, 0xca, v200
	v_med3_i32 v95, v90, 0, v216
	v_med3_i32 v90, v90, s46, v217
	v_add_u32_e32 v165, 0xd1, v200
	v_lshl_add_u32 v96, v90, 2, s15
	v_add_u32_e32 v90, 0xcb, v200
	v_med3_i32 v182, v165, 0, v216
	v_med3_i32 v165, v165, s46, v217
	v_med3_i32 v97, v90, 0, v216
	v_med3_i32 v90, v90, s46, v217
	v_lshl_add_u32 v184, v165, 2, s15
	v_add_u32_e32 v165, 0xd2, v200
	v_lshl_add_u32 v91, v91, 2, s15
	v_lshl_add_u32 v93, v93, 2, s15
	v_lshl_add_u32 v95, v95, 2, s15
	v_lshl_add_u32 v97, v97, 2, s15
	v_lshl_add_u32 v162, v90, 2, s15
	v_lshl_add_u32 v183, v182, 2, s15
	v_med3_i32 v182, v165, 0, v216
	v_med3_i32 v165, v165, s46, v217
	ds_read_b32 v90, v91
	ds_read_b32 v92, v92 offset:128
	ds_read_b32 v91, v93
	ds_read_b32 v93, v94 offset:128
	ds_read_b32 v94, v95
	ds_read_b32 v96, v96 offset:128
	ds_read_b32 v95, v97
	ds_read_b32 v97, v162 offset:128
	v_add_u32_e32 v162, 0xd0, v200
	v_lshl_add_u32 v201, v165, 2, s15
	v_add_u32_e32 v165, 0xd3, v200
	v_med3_i32 v164, v162, 0, v216
	v_lshl_add_u32 v185, v182, 2, s15
	v_med3_i32 v182, v165, 0, v216
	v_med3_i32 v165, v165, s46, v217
	v_med3_i32 v162, v162, s46, v217
	v_lshl_add_u32 v164, v164, 2, s15
	v_lshl_add_u32 v203, v182, 2, s15
	v_lshl_add_u32 v204, v165, 2, s15
	v_lshl_add_u32 v162, v162, 2, s15
	ds_read_b32 v164, v164
	ds_read_b32 v182, v162 offset:128
	ds_read_b32 v165, v183
	ds_read_b32 v183, v184 offset:128
	ds_read_b32 v184, v185
	ds_read_b32 v202, v201 offset:128
	ds_read_b32 v185, v203
	ds_read_b32 v203, v204 offset:128
	v_add_u32_e32 v204, 0xd9, v200
	v_med3_i32 v205, v204, 0, v216
	v_med3_i32 v204, v204, s46, v217
	v_lshl_add_u32 v210, v204, 2, s15
	v_add_u32_e32 v204, 0xda, v200
	v_add_u32_e32 v162, 0xd8, v200
	v_med3_i32 v206, v204, 0, v216
	v_med3_i32 v204, v204, s46, v217
	v_add_u32_e32 v200, 0xdb, v200
	v_med3_i32 v201, v162, 0, v216
	v_lshl_add_u32 v208, v204, 2, s15
	v_med3_i32 v204, v200, 0, v216
	v_med3_i32 v200, v200, s46, v217
	v_med3_i32 v162, v162, s46, v217
	v_lshl_add_u32 v201, v201, 2, s15
	v_lshl_add_u32 v205, v205, 2, s15
	v_lshl_add_u32 v206, v206, 2, s15
	v_lshl_add_u32 v207, v204, 2, s15
	v_lshl_add_u32 v209, v200, 2, s15
	v_lshl_add_u32 v162, v162, 2, s15
	ds_read_b32 v200, v201
	ds_read_b32 v204, v162 offset:128
	ds_read_b32 v206, v206
	ds_read_b32 v207, v207
	ds_read_b32 v201, v205
	ds_read_b32 v209, v209 offset:128
	ds_read_b32 v208, v208 offset:128
	ds_read_b32 v205, v210 offset:128
	s_waitcnt lgkmcnt(4)
	v_pk_add_f32 v[112:113], v[112:113], v[206:207]
	s_waitcnt lgkmcnt(3)
	v_pk_add_f32 v[110:111], v[110:111], v[200:201]
	v_pk_add_f32 v[108:109], v[108:109], v[184:185]
	v_pk_add_f32 v[106:107], v[106:107], v[164:165]
	v_pk_add_f32 v[104:105], v[104:105], v[94:95]
	v_pk_add_f32 v[102:103], v[102:103], v[90:91]
	v_pk_add_f32 v[100:101], v[100:101], v[86:87]
	v_pk_add_f32 v[98:99], v[98:99], v[82:83]
	s_waitcnt lgkmcnt(1)
	v_pk_add_f32 v[80:81], v[80:81], v[208:209]
	s_waitcnt lgkmcnt(0)
	v_pk_add_f32 v[78:79], v[78:79], v[204:205]
	v_pk_add_f32 v[76:77], v[76:77], v[202:203]
	v_pk_add_f32 v[74:75], v[74:75], v[182:183]
	v_pk_add_f32 v[72:73], v[72:73], v[96:97]
	v_pk_add_f32 v[70:71], v[70:71], v[92:93]
	v_pk_add_f32 v[68:69], v[68:69], v[88:89]
	v_pk_add_f32 v[66:67], v[66:67], v[84:85]
